# stack: G_up epilogue drops DPP zero-inits, up_fixup neighbour loads issued together, first seam uses the XCD barrier
# speedup vs baseline: 1.0141x; 1.0086x over previous
; DI unsigned pk2(float lo, float hi) { f32x2 v = {lo, hi}; return __builtin_bit_cast(unsigned, __builtin_convertvector(v, bf16x2v)); }
; DI void up_fixup(ArgsRef a, int l) {
;     ...
;     for (int it = gtid; it < nstrips * 2 * (DFF / 4); it += NT) {
;         const int c4 = it % (DFF / 4), rw = it / (DFF / 4), sg = rw >> 1, last = rw & 1, ca = 4 * c4;
;         const bool first_of_seq = sg < MLAT / 64 ? (sg & 63) == 0 : ((sg - MLAT / 64) & 3) == 0;
;         const bool last_of_seq = sg < MLAT / 64 ? (sg & 63) == 63 : ((sg - MLAT / 64) & 3) == 3;
;         const bf16_t* cur = RAW + ((size_t)sg * 4 + (last ? 3 : 0)) * DFF2 + ca;
;         const bf16_t* up = last ? RAW + ((size_t)sg * 4 + 2) * DFF2 + ca : RAW + ((size_t)(sg - 1) * 4 + 3) * DFF2 + ca;
;         const bf16_t* dn = last ? RAW + ((size_t)(sg + 1) * 4 + 0) * DFF2 + ca : RAW + ((size_t)sg * 4 + 1) * DFF2 + ca;
;         const bool has_up = last || !first_of_seq, has_dn = !last || !last_of_seq;
;         const f32x4 z = {0.f, 0.f, 0.f, 0.f};
;         const f32x4 ca_ = ld4(cur), cg_ = ld4(cur + DFF);
;         const f32x4 ua_ = has_up ? ld4(up) : z, ug_ = has_up ? ld4(up + DFF) : z;
;         const f32x4 da_ = has_dn ? ld4(dn) : z, dg_ = has_dn ? ld4(dn + DFF) : z;
;         const f32x4 wa0 = *(const f32x4*)(cw + ca), wa1 = *(const f32x4*)(cw + DFF2 + ca), wa2 = *(const f32x4*)(cw + 2 * DFF2 + ca), ba = *(const f32x4*)(cb + ca);
;         const f32x4 wg0 = *(const f32x4*)(cw + DFF + ca), wg1 = *(const f32x4*)(cw + DFF2 + DFF + ca), wg2 = *(const f32x4*)(cw + 2 * DFF2 + DFF + ca), bg = *(const f32x4*)(cb + DFF + ca);
;         const f32x4 va = wa0 * ua_ + wa1 * ca_ + wa2 * da_ + ba, vg = wg0 * ug_ + wg1 * cg_ + wg2 * dg_ + bg;
;         float o[4];
; #pragma unroll
;         for (int j = 0; j < 4; ++j) o[j] = vg[j] * __builtin_amdgcn_rcpf(1.f + __builtin_amdgcn_exp2f(-vg[j] * LOG2E)) * va[j];
;         u32x2 w; w.x = pk2(o[0], o[1]); w.y = pk2(o[2], o[3]);
;         *(u32x2*)(ACT + (size_t)(64 * sg + (last ? 63 : 0)) * DFF + ca) = w;
.LBB0_50:
	s_or_b64 exec, exec, s[54:55]
	v_lshlrev_b64 v[52:53], 2, v[0:1]
	v_lshl_add_u64 v[40:41], s[18:19], 0, v[52:53]
	global_load_dwordx4 v[40:43], v[40:41], off
	v_lshl_add_u64 v[44:45], s[20:21], 0, v[52:53]
	global_load_dwordx4 v[44:47], v[44:45], off
	v_lshl_add_u64 v[48:49], s[24:25], 0, v[52:53]
	s_waitcnt vmcnt(0)
	v_lshlrev_b32_e32 v2, 16, v4
	v_and_b32_e32 v3, 0xffff0000, v4
	v_lshlrev_b32_e32 v4, 16, v5
	v_and_b32_e32 v5, 0xffff0000, v5
	v_lshlrev_b32_e32 v6, 16, v8
	v_and_b32_e32 v7, 0xffff0000, v8
	v_lshlrev_b32_e32 v8, 16, v9
	v_and_b32_e32 v9, 0xffff0000, v9
	v_lshlrev_b32_e32 v12, 16, v10
	v_and_b32_e32 v13, 0xffff0000, v10
	v_lshlrev_b32_e32 v10, 16, v11
	v_and_b32_e32 v11, 0xffff0000, v11
	v_lshlrev_b32_e32 v14, 16, v16
	v_and_b32_e32 v15, 0xffff0000, v16
	v_lshlrev_b32_e32 v16, 16, v17
	v_and_b32_e32 v17, 0xffff0000, v17
	v_lshlrev_b32_e32 v58, 16, v18
	v_and_b32_e32 v59, 0xffff0000, v18
	v_lshlrev_b32_e32 v60, 16, v19
	v_and_b32_e32 v61, 0xffff0000, v19
	v_lshl_add_u64 v[18:19], s[10:11], 0, v[52:53]
	v_lshl_add_u64 v[28:29], s[14:15], 0, v[52:53]
	v_lshl_add_u64 v[32:33], s[16:17], 0, v[52:53]
	v_lshl_add_u64 v[36:37], s[12:13], 0, v[52:53]
	global_load_dwordx4 v[48:51], v[48:49], off
	v_lshl_add_u64 v[52:53], s[44:45], 0, v[52:53]
	global_load_dwordx4 v[52:55], v[52:53], off
	v_lshlrev_b32_e32 v22, 16, v20
	v_and_b32_e32 v23, 0xffff0000, v20
	v_lshlrev_b32_e32 v56, 16, v21
	v_and_b32_e32 v57, 0xffff0000, v21
	global_load_dwordx4 v[18:21], v[18:19], off
	v_add_u32_e32 v24, s34, v24
	global_load_dwordx4 v[28:31], v[28:29], off
	v_cmp_le_i32_e32 vcc, s26, v24
	global_load_dwordx4 v[32:35], v[32:33], off
	s_or_b64 s[46:47], vcc, s[46:47]
	global_load_dwordx4 v[36:39], v[36:37], off
	s_waitcnt vmcnt(7)
	v_pk_mul_f32 v[6:7], v[6:7], v[40:41]
	v_pk_mul_f32 v[8:9], v[8:9], v[42:43]
	s_waitcnt vmcnt(6)
	v_pk_fma_f32 v[6:7], v[44:45], v[58:59], v[6:7]
	s_waitcnt vmcnt(3)
	v_pk_mul_f32 v[2:3], v[2:3], v[18:19]
	v_pk_fma_f32 v[6:7], v[14:15], v[48:49], v[6:7]
	s_waitcnt vmcnt(2)
	v_pk_fma_f32 v[2:3], v[28:29], v[22:23], v[2:3]
	v_pk_add_f32 v[6:7], v[52:53], v[6:7]
	s_waitcnt vmcnt(1)
	v_pk_fma_f32 v[2:3], v[12:13], v[32:33], v[2:3]
	v_mul_f32_e32 v14, 0xbfb8aa3b, v6
	v_mul_f32_e32 v15, 0xbfb8aa3b, v7
	v_exp_f32_e32 v14, v14
	v_exp_f32_e32 v15, v15
	s_waitcnt vmcnt(0)
	v_pk_add_f32 v[2:3], v[36:37], v[2:3]
	v_pk_mul_f32 v[4:5], v[4:5], v[20:21]
	v_add_f32_e32 v14, 1.0, v14
	v_add_f32_e32 v15, 1.0, v15
	v_rcp_f32_e32 v14, v14
	v_rcp_f32_e32 v15, v15
	v_pk_fma_f32 v[4:5], v[30:31], v[56:57], v[4:5]
	v_pk_mul_f32 v[6:7], v[6:7], v[14:15]
	s_nop 0
	v_pk_mul_f32 v[2:3], v[2:3], v[6:7]
	v_pk_fma_f32 v[6:7], v[46:47], v[60:61], v[8:9]
	v_pk_fma_f32 v[4:5], v[10:11], v[34:35], v[4:5]
	v_pk_fma_f32 v[6:7], v[16:17], v[50:51], v[6:7]
	v_pk_add_f32 v[4:5], v[38:39], v[4:5]
	v_pk_add_f32 v[6:7], v[54:55], v[6:7]
	v_cvt_pk_bf16_f32 v2, v2, v3
	v_mul_f32_e32 v8, 0xbfb8aa3b, v6
	v_mul_f32_e32 v9, 0xbfb8aa3b, v7
	v_exp_f32_e32 v8, v8
	v_exp_f32_e32 v9, v9
	v_add_f32_e32 v8, 1.0, v8
	v_add_f32_e32 v9, 1.0, v9
	v_rcp_f32_e32 v8, v8
	v_rcp_f32_e32 v9, v9
	s_nop 0
	v_pk_mul_f32 v[6:7], v[6:7], v[8:9]
	s_nop 0
	v_pk_mul_f32 v[4:5], v[4:5], v[6:7]
	s_nop 0
	v_cvt_pk_bf16_f32 v3, v4, v5
	v_cndmask_b32_e64 v4, 0, 63, s[6:7]
	v_readlane_b32 s6, v254, 39
	v_readlane_b32 s7, v254, 40
	v_lshl_or_b32 v6, v26, 6, v4
	s_nop 0
	v_mov_b64_e32 v[4:5], s[6:7]
	s_movk_i32 s6, 0x2c00
	v_mad_i64_i32 v[4:5], s[6:7], v6, s6, v[4:5]
	v_readlane_b32 s6, v254, 1
	v_lshl_add_u64 v[0:1], v[0:1], 1, v[4:5]
	global_store_dwordx2 v[0:1], v[2:3], off
	v_add_u32_e32 v25, s6, v25
	s_andn2_b64 exec, exec, s[46:47]
	s_cbranch_execz .LBB0_63
.LBB0_51:
	s_mov_b32 s6, 0x2e8ba2e9
	v_mul_hi_i32 v0, v24, s6
	v_lshrrev_b32_e32 v1, 31, v0
	v_ashrrev_i32_e32 v0, 8, v0
	v_add_u32_e32 v3, v0, v1
	v_and_b32_e32 v2, 1, v3
	v_ashrrev_i32_e32 v26, 1, v3
	v_cmp_eq_u32_e64 s[6:7], 1, v2
	v_cmp_eq_u32_e32 vcc, 0, v2
	s_and_saveexec_b64 s[8:9], vcc
	s_xor_b64 s[8:9], exec, s[8:9]
	v_mul_hi_i32_i24_e32 v1, 0x16000, v26
	v_mul_i32_i24_e32 v0, 0x16000, v26
	v_lshl_add_u64 v[0:1], s[36:37], 0, v[0:1]
	s_mov_b64 s[40:41], 0x5800
	v_lshl_add_u64 v[10:11], v[0:1], 0, s[40:41]
	s_andn2_saveexec_b64 s[8:9], s[8:9]
	v_add_u32_e32 v0, 1, v26
	v_mul_hi_i32_i24_e32 v1, 0x16000, v0
	v_mul_i32_i24_e32 v0, 0x16000, v0
	v_lshl_add_u64 v[10:11], s[36:37], 0, v[0:1]
	s_or_b64 exec, exec, s[8:9]
	v_mul_i32_i24_e32 v0, 0x580, v3
	v_lshlrev_b32_e32 v0, 2, v0
	v_cndmask_b32_e64 v1, 0, 3, s[6:7]
	v_sub_u32_e32 v0, v25, v0
	v_lshl_or_b32 v1, v26, 2, v1
	v_mul_hi_i32_i24_e32 v5, 0x5800, v1
	v_mul_i32_i24_e32 v4, 0x5800, v1
	v_ashrrev_i32_e32 v1, 31, v0
	v_lshl_add_u64 v[4:5], s[36:37], 0, v[4:5]
	v_lshlrev_b64 v[6:7], 1, v[0:1]
	v_lshl_add_u64 v[4:5], v[4:5], 0, v[6:7]
	v_add_co_u32_e32 v8, vcc, 0x2000, v4
	s_movk_i32 s8, 0x200
	s_nop 0
	v_addc_co_u32_e32 v9, vcc, 0, v5, vcc
	global_load_dwordx2 v[20:21], v[4:5], off
	global_load_dwordx2 v[18:19], v[8:9], off offset:3072
	v_add_u32_e32 v4, -1, v26
	v_mov_b32_e32 v5, 0x10800
	v_mov_b32_e32 v8, 0xb000
	v_cndmask_b32_e64 v4, v4, v26, s[6:7]
	v_and_b32_e32 v15, 0x7e, v3
	v_and_b32_e32 v14, 6, v3
	v_cmp_gt_i32_e64 s[8:9], s8, v26
	v_cndmask_b32_e64 v184, v5, v8, s[6:7]
	v_mul_hi_i32_i24_e32 v5, 0x16000, v4
	v_mul_i32_i24_e32 v4, 0x16000, v4
	v_cndmask_b32_e64 v3, v14, v15, s[8:9]
	v_lshl_add_u64 v[4:5], s[36:37], 0, v[4:5]
	v_lshl_add_u64 v[4:5], v[4:5], 0, v[184:185]
	v_or_b32_e32 v2, v3, v2
	v_lshl_add_u64 v[12:13], v[4:5], 0, v[6:7]
	v_cmp_ne_u32_e32 vcc, 0, v2
	v_mov_b32_e32 v4, 0
	v_mov_b32_e32 v5, 0
	v_mov_b32_e32 v8, 0
	v_mov_b32_e32 v9, 0
	s_and_saveexec_b64 s[54:55], vcc
	global_load_dwordx2 v[4:5], v[12:13], off
	v_add_co_u32_e32 v6, vcc, 0x2000, v12
	s_nop 1
	v_addc_co_u32_e32 v7, vcc, 0, v13, vcc
	global_load_dwordx2 v[8:9], v[6:7], off offset:3072
	s_or_b64 exec, exec, s[54:55]
	s_movk_i32 s27, 0x7e
	v_cmp_eq_u32_e32 vcc, s27, v15
	v_lshl_add_u64 v[22:23], v[0:1], 1, v[10:11]
	v_mov_b32_e32 v10, 0
	v_cndmask_b32_e64 v12, 0, 1, vcc
	v_cmp_eq_u32_e32 vcc, 6, v14
	v_mov_b32_e32 v14, 0
	v_mov_b32_e32 v11, 0
	v_cndmask_b32_e64 v13, 0, 1, vcc
	v_cndmask_b32_e64 v12, v13, v12, s[8:9]
	v_and_b32_e32 v12, 1, v12
	v_cmp_eq_u32_e32 vcc, 1, v12
	s_and_b64 s[8:9], s[6:7], vcc
	s_xor_b64 s[8:9], s[8:9], -1
	v_mov_b32_e32 v16, 0
	v_mov_b32_e32 v17, 0
	s_and_saveexec_b64 s[54:55], s[8:9]
	global_load_dwordx2 v[10:11], v[22:23], off
	v_add_co_u32_e32 v14, vcc, 0x2000, v22
	s_nop 1
	v_addc_co_u32_e32 v15, vcc, 0, v23, vcc
	global_load_dwordx2 v[16:17], v[14:15], off offset:3072
	s_branch .LBB0_50

; DI unsigned pk2(float lo, float hi) { f32x2 v = {lo, hi}; return __builtin_bit_cast(unsigned, __builtin_convertvector(v, bf16x2v)); }
; DI float dpp_ror1(float v) { return __builtin_bit_cast(float, __builtin_amdgcn_update_dpp(0, __builtin_bit_cast(int, v), 0x121, 0xF, 0xF, false)); }
; DI float dpp_rol1(float v) { return __builtin_bit_cast(float, __builtin_amdgcn_update_dpp(0, __builtin_bit_cast(int, v), 0x12F, 0xF, 0xF, false)); }
;     DI void operator()(const f32x4 (&acc)[2][2][4][2], const Unit& u, int wr, int wc, int fr, int fq) const {
;     ...
;             for (int ai = 0; ai < 2; ++ai) {
;                 const int sg = 4 * u.pm + 2 * ai + wr, row0 = 64 * sg;
; #pragma unroll
;                 for (int m = 0; m < 4; ++m) {
;                     const int rho = 16 * m + fr;
;                     const f32x4 ca_ = acc[ai][0][m][n], cg_ = acc[ai][1][m][n];
;                     const f32x4 ua_ = acc[ai][0][m > 0 ? m - 1 : 0][n], ug_ = acc[ai][1][m > 0 ? m - 1 : 0][n];
;                     const f32x4 da_ = acc[ai][0][m < 3 ? m + 1 : 3][n], dg_ = acc[ai][1][m < 3 ? m + 1 : 3][n];
;                     float o[4];
; #pragma unroll
;                     for (int j = 0; j < 4; ++j) {
;                         const float upa = dpp_ror1(fr == 15 ? ua_[j] : ca_[j]), dna = dpp_rol1(fr == 0 ? da_[j] : ca_[j]);
;                         const float upg = dpp_ror1(fr == 15 ? ug_[j] : cg_[j]), dng = dpp_rol1(fr == 0 ? dg_[j] : cg_[j]);
;                         const float va = wa0[j] * upa + wa1[j] * ca_[j] + wa2[j] * dna + ba[j];
;                         const float vg = wg0[j] * upg + wg1[j] * cg_[j] + wg2[j] * dng + bg[j];
;                         const float sgm = vg * __builtin_amdgcn_rcpf(1.f + __builtin_amdgcn_exp2f(-vg * LOG2E));
;                         o[j] = sgm * va;
;                     }
;                     if (rho >= 1 && rho <= 62) { u32x2 w; w.x = pk2(o[0], o[1]); w.y = pk2(o[2], o[3]); *(u32x2*)(ACT + (size_t)(row0 + rho) * DFF + ca) = w; }
.LBB0_113:
	v_readlane_b32 s0, v254, 52
	v_readlane_b32 s44, v255, 2
	v_readlane_b32 s45, v255, 3
	v_lshl_or_b32 v162, s0, 7, v211
	v_ashrrev_i32_e32 v163, 31, v162
	v_lshlrev_b64 v[148:149], 2, v[162:163]
	v_lshl_add_u64 v[164:165], s[44:45], 0, v[148:149]
	v_readlane_b32 s44, v255, 4
	v_readlane_b32 s45, v255, 5
	v_lshl_add_u64 v[132:133], s[80:81], 0, v[148:149]
	v_lshl_add_u64 v[134:135], s[70:71], 0, v[148:149]
	v_readlane_b32 s44, v255, 1
	s_nop 3
	s_and_b32 s44, s44, 1
	s_lshl_b32 s44, s44, 12
	s_add_i32 s44, s44, 0x20100
	v_lshl_add_u32 v166, v211, 2, s44
	v_lshl_add_u64 v[140:141], s[24:25], 0, v[148:149]
	v_lshl_add_u64 v[144:145], s[72:73], 0, v[148:149]
	ds_read_b128 v[128:131], v166
	ds_read_b128 v[156:159], v166 offset:512
	s_nop 0
	ds_read_b128 v[132:135], v166 offset:1024
	v_cndmask_b32_e64 v168, v124, v116, s[10:11]
	ds_read_b128 v[136:139], v166 offset:1536
	s_nop 0
	ds_read_b128 v[140:143], v166 offset:2048
	s_nop 0
	ds_read_b128 v[152:155], v166 offset:2560
	v_lshl_add_u64 v[144:145], s[66:67], 0, v[148:149]
	v_lshl_add_u64 v[148:149], s[68:69], 0, v[148:149]
	ds_read_b128 v[144:147], v166 offset:3072
	ds_read_b128 v[148:151], v166 offset:3584
	v_mov_b32_dpp v174, v168 row_ror:15 row_mask:0xf bank_mask:0xf
	v_cndmask_b32_e64 v168, v92, v84, s[10:11]
	s_lshl_b32 s0, s26, 2
	v_readlane_b32 s40, v254, 62
	v_mov_b32_dpp v182, v168 row_ror:15 row_mask:0xf bank_mask:0xf
	v_cndmask_b32_e64 v168, v125, v117, s[10:11]
	v_cndmask_b32_e64 v169, v126, v118, s[10:11]
	s_add_i32 s54, s0, s40
	v_mov_b32_dpp v175, v168 row_ror:15 row_mask:0xf bank_mask:0xf
	v_cndmask_b32_e64 v168, v93, v85, s[10:11]
	v_mov_b32_dpp v170, v169 row_ror:15 row_mask:0xf bank_mask:0xf
	v_cndmask_b32_e64 v169, v94, v86, s[10:11]
	v_cndmask_b32_e64 v177, v127, v119, s[10:11]
	s_lshl_b32 s90, s54, 6
	v_mov_b32_dpp v183, v168 row_ror:15 row_mask:0xf bank_mask:0xf
	v_mov_b32_dpp v176, v169 row_ror:15 row_mask:0xf bank_mask:0xf
	v_mov_b32_dpp v171, v177 row_ror:15 row_mask:0xf bank_mask:0xf
	v_cndmask_b32_e64 v194, v95, v87, s[10:11]
	v_mov_b32_dpp v172, v124 row_ror:1 row_mask:0xf bank_mask:0xf
	v_mov_b32_dpp v180, v92 row_ror:1 row_mask:0xf bank_mask:0xf
	v_mov_b32_dpp v173, v125 row_ror:1 row_mask:0xf bank_mask:0xf
	v_mov_b32_dpp v181, v93 row_ror:1 row_mask:0xf bank_mask:0xf
	v_mov_b32_dpp v168, v126 row_ror:1 row_mask:0xf bank_mask:0xf
	v_mov_b32_dpp v178, v94 row_ror:1 row_mask:0xf bank_mask:0xf
	v_mov_b32_dpp v169, v127 row_ror:1 row_mask:0xf bank_mask:0xf
	v_mov_b32_dpp v179, v95 row_ror:1 row_mask:0xf bank_mask:0xf
	v_mov_b32_dpp v177, v194 row_ror:15 row_mask:0xf bank_mask:0xf
	v_or_b32_e32 v215, s90, v160
	s_and_saveexec_b64 s[44:45], s[12:13]
	s_cbranch_execz .LBB0_115
	s_waitcnt lgkmcnt(0)
	v_pk_mul_f32 v[198:199], v[92:93], v[152:153]
	v_pk_mul_f32 v[196:197], v[124:125], v[156:157]
	v_pk_fma_f32 v[180:181], v[140:141], v[180:181], v[198:199]
	v_pk_fma_f32 v[172:173], v[128:129], v[172:173], v[196:197]
	v_pk_fma_f32 v[180:181], v[144:145], v[182:183], v[180:181]
	v_pk_fma_f32 v[172:173], v[132:133], v[174:175], v[172:173]
	v_pk_add_f32 v[180:181], v[148:149], v[180:181]
	v_pk_add_f32 v[172:173], v[136:137], v[172:173]
	v_mul_f32_e32 v182, 0xbfb8aa3b, v180
	v_exp_f32_e32 v198, v182
	v_mul_f32_e32 v182, 0xbfb8aa3b, v181
	v_exp_f32_e32 v199, v182
	v_pk_mul_f32 v[182:183], v[94:95], v[154:155]
	v_add_f32_e32 v198, 1.0, v198
	v_pk_fma_f32 v[178:179], v[142:143], v[178:179], v[182:183]
	v_add_f32_e32 v199, 1.0, v199
	v_pk_fma_f32 v[176:177], v[146:147], v[176:177], v[178:179]
	v_rcp_f32_e32 v198, v198
	v_pk_add_f32 v[176:177], v[150:151], v[176:177]
	v_rcp_f32_e32 v199, v199
	v_mul_f32_e32 v178, 0xbfb8aa3b, v176
	v_mul_f32_e32 v179, 0xbfb8aa3b, v177
	v_exp_f32_e32 v178, v178
	v_exp_f32_e32 v179, v179
	v_pk_mul_f32 v[174:175], v[180:181], v[198:199]
	v_pk_mul_f32 v[194:195], v[126:127], v[158:159]
	v_pk_mul_f32 v[172:173], v[172:173], v[174:175]
	v_add_f32_e32 v174, 1.0, v178
	v_add_f32_e32 v175, 1.0, v179
	v_rcp_f32_e32 v174, v174
	v_rcp_f32_e32 v175, v175
	v_pk_fma_f32 v[168:169], v[130:131], v[168:169], v[194:195]
	v_readlane_b32 s46, v254, 39
	v_pk_fma_f32 v[168:169], v[134:135], v[170:171], v[168:169]
	v_pk_mul_f32 v[170:171], v[176:177], v[174:175]
	v_pk_add_f32 v[168:169], v[138:139], v[168:169]
	v_readlane_b32 s47, v254, 40
	v_pk_mul_f32 v[168:169], v[168:169], v[170:171]
	s_movk_i32 s0, 0x2c00
	v_cvt_pk_bf16_f32 v171, v168, v169
	v_mov_b64_e32 v[168:169], s[46:47]
	v_mad_i64_i32 v[168:169], s[46:47], v215, s0, v[168:169]
	v_cvt_pk_bf16_f32 v170, v172, v173
	v_lshl_add_u64 v[168:169], v[162:163], 1, v[168:169]
	global_store_dwordx2 v[168:169], v[170:171], off

; DI unsigned pk2(float lo, float hi) { f32x2 v = {lo, hi}; return __builtin_bit_cast(unsigned, __builtin_convertvector(v, bf16x2v)); }
; DI float dpp_ror1(float v) { return __builtin_bit_cast(float, __builtin_amdgcn_update_dpp(0, __builtin_bit_cast(int, v), 0x121, 0xF, 0xF, false)); }
; DI float dpp_rol1(float v) { return __builtin_bit_cast(float, __builtin_amdgcn_update_dpp(0, __builtin_bit_cast(int, v), 0x12F, 0xF, 0xF, false)); }
;     DI void operator()(const f32x4 (&acc)[2][2][4][2], const Unit& u, int wr, int wc, int fr, int fq) const {
;     ...
;                 for (int m = 0; m < 4; ++m) {
;                     const int rho = 16 * m + fr;
;                     const f32x4 ca_ = acc[ai][0][m][n], cg_ = acc[ai][1][m][n];
;                     const f32x4 ua_ = acc[ai][0][m > 0 ? m - 1 : 0][n], ug_ = acc[ai][1][m > 0 ? m - 1 : 0][n];
;                     const f32x4 da_ = acc[ai][0][m < 3 ? m + 1 : 3][n], dg_ = acc[ai][1][m < 3 ? m + 1 : 3][n];
;                     float o[4];
; #pragma unroll
;                     for (int j = 0; j < 4; ++j) {
;                         const float upa = dpp_ror1(fr == 15 ? ua_[j] : ca_[j]), dna = dpp_rol1(fr == 0 ? da_[j] : ca_[j]);
;                         const float upg = dpp_ror1(fr == 15 ? ug_[j] : cg_[j]), dng = dpp_rol1(fr == 0 ? dg_[j] : cg_[j]);
;                         const float va = wa0[j] * upa + wa1[j] * ca_[j] + wa2[j] * dna + ba[j];
;                         const float vg = wg0[j] * upg + wg1[j] * cg_[j] + wg2[j] * dng + bg[j];
;                         const float sgm = vg * __builtin_amdgcn_rcpf(1.f + __builtin_amdgcn_exp2f(-vg * LOG2E));
;                         o[j] = sgm * va;
;                     }
;                     if (rho >= 1 && rho <= 62) { u32x2 w; w.x = pk2(o[0], o[1]); w.y = pk2(o[2], o[3]); *(u32x2*)(ACT + (size_t)(row0 + rho) * DFF + ca) = w; }
.LBB0_117:
	s_or_b64 exec, exec, s[56:57]
	v_cndmask_b32_e64 v169, v116, v124, s[6:7]
	s_nop 1
	v_mov_b32_dpp v168, v169 row_ror:1 row_mask:0xf bank_mask:0xf
	v_cndmask_b32_e64 v169, v116, v108, s[10:11]
	v_cndmask_b32_e64 v171, v117, v125, s[6:7]
	s_nop 0
	v_mov_b32_dpp v170, v169 row_ror:15 row_mask:0xf bank_mask:0xf
	v_cndmask_b32_e64 v169, v84, v92, s[6:7]
	v_cndmask_b32_e64 v173, v117, v109, s[10:11]
	v_cndmask_b32_e64 v175, v85, v93, s[6:7]
	v_mov_b32_dpp v172, v169 row_ror:1 row_mask:0xf bank_mask:0xf
	v_cndmask_b32_e64 v169, v84, v76, s[10:11]
	v_cndmask_b32_e64 v176, v85, v77, s[10:11]
	s_waitcnt lgkmcnt(0)
	v_pk_mul_f32 v[200:201], v[84:85], v[152:153]
	v_mov_b32_dpp v174, v169 row_ror:15 row_mask:0xf bank_mask:0xf
	v_pk_mul_f32 v[196:197], v[116:117], v[156:157]
	v_cndmask_b32_e64 v177, v118, v126, s[6:7]
	v_mov_b32_dpp v169, v171 row_ror:1 row_mask:0xf bank_mask:0xf
	v_pk_fma_f32 v[168:169], v[128:129], v[168:169], v[196:197]
	v_mov_b32_dpp v171, v173 row_ror:15 row_mask:0xf bank_mask:0xf
	v_pk_fma_f32 v[168:169], v[132:133], v[170:171], v[168:169]
	v_mov_b32_dpp v173, v175 row_ror:1 row_mask:0xf bank_mask:0xf
	v_pk_fma_f32 v[172:173], v[140:141], v[172:173], v[200:201]
	v_mov_b32_dpp v175, v176 row_ror:15 row_mask:0xf bank_mask:0xf
	v_pk_fma_f32 v[172:173], v[144:145], v[174:175], v[172:173]
	v_pk_add_f32 v[172:173], v[148:149], v[172:173]
	v_cndmask_b32_e64 v179, v119, v127, s[6:7]
	v_mul_f32_e32 v174, 0xbfb8aa3b, v172
	v_mul_f32_e32 v170, 0xbfb8aa3b, v173
	v_exp_f32_e32 v174, v174
	v_exp_f32_e32 v170, v170
	v_mov_b32_dpp v176, v177 row_ror:1 row_mask:0xf bank_mask:0xf
	v_cndmask_b32_e64 v177, v118, v110, s[10:11]
	v_add_f32_e32 v174, 1.0, v174
	v_add_f32_e32 v170, 1.0, v170
	v_mov_b32_dpp v178, v177 row_ror:15 row_mask:0xf bank_mask:0xf
	v_cndmask_b32_e64 v177, v86, v94, s[6:7]
	v_rcp_f32_e32 v174, v174
	v_rcp_f32_e32 v175, v170
	v_mov_b32_dpp v180, v177 row_ror:1 row_mask:0xf bank_mask:0xf
	v_cndmask_b32_e64 v177, v86, v78, s[10:11]
	v_cndmask_b32_e64 v181, v119, v111, s[10:11]
	v_cndmask_b32_e64 v183, v87, v95, s[6:7]
	v_mov_b32_dpp v182, v177 row_ror:15 row_mask:0xf bank_mask:0xf
	v_cndmask_b32_e64 v194, v87, v79, s[10:11]
	v_pk_mul_f32 v[198:199], v[86:87], v[154:155]
	v_mov_b32_dpp v177, v179 row_ror:1 row_mask:0xf bank_mask:0xf
	v_pk_add_f32 v[168:169], v[136:137], v[168:169]
	v_pk_mul_f32 v[170:171], v[172:173], v[174:175]
	v_mov_b32_dpp v179, v181 row_ror:15 row_mask:0xf bank_mask:0xf
	v_pk_mul_f32 v[168:169], v[168:169], v[170:171]
	v_readlane_b32 s46, v254, 39
	v_mov_b32_dpp v181, v183 row_ror:1 row_mask:0xf bank_mask:0xf
	v_pk_fma_f32 v[170:171], v[142:143], v[180:181], v[198:199]
	v_readlane_b32 s47, v254, 40
	v_mov_b32_dpp v183, v194 row_ror:15 row_mask:0xf bank_mask:0xf
	v_pk_fma_f32 v[170:171], v[146:147], v[182:183], v[170:171]
	v_pk_mul_f32 v[194:195], v[118:119], v[158:159]
	v_pk_add_f32 v[170:171], v[150:151], v[170:171]
	v_pk_fma_f32 v[174:175], v[130:131], v[176:177], v[194:195]
	v_mul_f32_e32 v172, 0xbfb8aa3b, v170
	v_mul_f32_e32 v173, 0xbfb8aa3b, v171
	v_exp_f32_e32 v172, v172
	v_exp_f32_e32 v173, v173
	v_pk_fma_f32 v[174:175], v[134:135], v[178:179], v[174:175]
	s_movk_i32 s0, 0x2c00
	v_add_f32_e32 v172, 1.0, v172
	v_add_f32_e32 v173, 1.0, v173
	v_rcp_f32_e32 v172, v172
	v_rcp_f32_e32 v173, v173
	v_pk_add_f32 v[174:175], v[138:139], v[174:175]
	v_lshlrev_b64 v[176:177], 1, v[162:163]
	v_pk_mul_f32 v[170:171], v[170:171], v[172:173]
	v_cvt_pk_bf16_f32 v172, v168, v169
	v_pk_mul_f32 v[170:171], v[174:175], v[170:171]
	v_or_b32_e32 v168, s90, v208
	v_cvt_pk_bf16_f32 v173, v170, v171
	v_mov_b64_e32 v[170:171], s[46:47]
	v_mad_i64_i32 v[168:169], s[46:47], v168, s0, v[170:171]
	v_lshl_add_u64 v[168:169], v[168:169], 0, v[176:177]
	global_store_dwordx2 v[168:169], v[172:173], off
	v_cndmask_b32_e64 v173, v108, v116, s[6:7]
	s_nop 1
	v_mov_b32_dpp v172, v173 row_ror:1 row_mask:0xf bank_mask:0xf
	v_cndmask_b32_e64 v173, v108, v100, s[10:11]
	v_cndmask_b32_e64 v175, v109, v117, s[6:7]
	v_cndmask_b32_e64 v179, v109, v101, s[10:11]
	v_mov_b32_dpp v174, v173 row_ror:15 row_mask:0xf bank_mask:0xf
	v_cndmask_b32_e64 v173, v76, v84, s[6:7]
	v_cndmask_b32_e64 v181, v77, v85, s[6:7]
	v_cndmask_b32_e64 v182, v77, v69, s[10:11]
	v_mov_b32_dpp v178, v173 row_ror:1 row_mask:0xf bank_mask:0xf
	v_cndmask_b32_e64 v173, v76, v68, s[10:11]
	v_pk_mul_f32 v[202:203], v[76:77], v[152:153]
	v_pk_mul_f32 v[218:219], v[108:109], v[156:157]
	v_mov_b32_dpp v180, v173 row_ror:15 row_mask:0xf bank_mask:0xf
	v_cndmask_b32_e64 v183, v110, v118, s[6:7]
	v_mov_b32_dpp v173, v175 row_ror:1 row_mask:0xf bank_mask:0xf
	v_pk_fma_f32 v[172:173], v[128:129], v[172:173], v[218:219]
	v_mov_b32_dpp v175, v179 row_ror:15 row_mask:0xf bank_mask:0xf
	v_pk_fma_f32 v[172:173], v[132:133], v[174:175], v[172:173]
	v_mov_b32_dpp v179, v181 row_ror:1 row_mask:0xf bank_mask:0xf
	v_pk_fma_f32 v[178:179], v[140:141], v[178:179], v[202:203]
	v_cndmask_b32_e64 v195, v111, v119, s[6:7]
	v_mov_b32_dpp v181, v182 row_ror:15 row_mask:0xf bank_mask:0xf
	v_pk_fma_f32 v[178:179], v[144:145], v[180:181], v[178:179]
	v_pk_add_f32 v[178:179], v[148:149], v[178:179]
	v_cndmask_b32_e64 v197, v111, v103, s[10:11]
	v_mul_f32_e32 v180, 0xbfb8aa3b, v178
	v_mul_f32_e32 v174, 0xbfb8aa3b, v179
	v_exp_f32_e32 v180, v180
	v_exp_f32_e32 v174, v174
	v_mov_b32_dpp v182, v183 row_ror:1 row_mask:0xf bank_mask:0xf
; DI unsigned pk2(float lo, float hi) { f32x2 v = {lo, hi}; return __builtin_bit_cast(unsigned, __builtin_convertvector(v, bf16x2v)); }
; DI float dpp_ror1(float v) { return __builtin_bit_cast(float, __builtin_amdgcn_update_dpp(0, __builtin_bit_cast(int, v), 0x121, 0xF, 0xF, false)); }
; DI float dpp_rol1(float v) { return __builtin_bit_cast(float, __builtin_amdgcn_update_dpp(0, __builtin_bit_cast(int, v), 0x12F, 0xF, 0xF, false)); }
;     DI void operator()(const f32x4 (&acc)[2][2][4][2], const Unit& u, int wr, int wc, int fr, int fq) const {
;     ...
;                 for (int m = 0; m < 4; ++m) {
;                     const int rho = 16 * m + fr;
;                     const f32x4 ca_ = acc[ai][0][m][n], cg_ = acc[ai][1][m][n];
;                     const f32x4 ua_ = acc[ai][0][m > 0 ? m - 1 : 0][n], ug_ = acc[ai][1][m > 0 ? m - 1 : 0][n];
;                     const f32x4 da_ = acc[ai][0][m < 3 ? m + 1 : 3][n], dg_ = acc[ai][1][m < 3 ? m + 1 : 3][n];
;                     float o[4];
; #pragma unroll
;                     for (int j = 0; j < 4; ++j) {
;                         const float upa = dpp_ror1(fr == 15 ? ua_[j] : ca_[j]), dna = dpp_rol1(fr == 0 ? da_[j] : ca_[j]);
;                         const float upg = dpp_ror1(fr == 15 ? ug_[j] : cg_[j]), dng = dpp_rol1(fr == 0 ? dg_[j] : cg_[j]);
;                         const float va = wa0[j] * upa + wa1[j] * ca_[j] + wa2[j] * dna + ba[j];
;                         const float vg = wg0[j] * upg + wg1[j] * cg_[j] + wg2[j] * dng + bg[j];
;                         const float sgm = vg * __builtin_amdgcn_rcpf(1.f + __builtin_amdgcn_exp2f(-vg * LOG2E));
;                         o[j] = sgm * va;
;                     }
;                     if (rho >= 1 && rho <= 62) { u32x2 w; w.x = pk2(o[0], o[1]); w.y = pk2(o[2], o[3]); *(u32x2*)(ACT + (size_t)(row0 + rho) * DFF + ca) = w; }
	v_cndmask_b32_e64 v183, v110, v102, s[10:11]
	v_add_f32_e32 v180, 1.0, v180
	v_add_f32_e32 v174, 1.0, v174
	v_mov_b32_dpp v194, v183 row_ror:15 row_mask:0xf bank_mask:0xf
	v_cndmask_b32_e64 v183, v78, v86, s[6:7]
	v_rcp_f32_e32 v180, v180
	v_rcp_f32_e32 v181, v174
	v_mov_b32_dpp v196, v183 row_ror:1 row_mask:0xf bank_mask:0xf
	v_cndmask_b32_e64 v183, v78, v70, s[10:11]
	v_cndmask_b32_e64 v199, v79, v87, s[6:7]
	v_cndmask_b32_e64 v200, v79, v71, s[10:11]
	v_mov_b32_dpp v198, v183 row_ror:15 row_mask:0xf bank_mask:0xf
	v_pk_add_f32 v[172:173], v[136:137], v[172:173]
	v_pk_mul_f32 v[174:175], v[178:179], v[180:181]
	v_mov_b32_dpp v183, v195 row_ror:1 row_mask:0xf bank_mask:0xf
	v_pk_mul_f32 v[172:173], v[172:173], v[174:175]
	v_pk_mul_f32 v[202:203], v[110:111], v[158:159]
	v_mov_b32_dpp v195, v197 row_ror:15 row_mask:0xf bank_mask:0xf
	v_pk_fma_f32 v[180:181], v[130:131], v[182:183], v[202:203]
	v_mov_b32_dpp v197, v199 row_ror:1 row_mask:0xf bank_mask:0xf
	v_pk_fma_f32 v[180:181], v[134:135], v[194:195], v[180:181]
	v_cndmask_b32_e64 v195, v71, v79, s[6:7]
	v_mov_b32_dpp v199, v200 row_ror:15 row_mask:0xf bank_mask:0xf
	v_pk_mul_f32 v[200:201], v[78:79], v[154:155]
	v_pk_add_f32 v[180:181], v[138:139], v[180:181]
	v_pk_fma_f32 v[174:175], v[142:143], v[196:197], v[200:201]
	v_pk_fma_f32 v[174:175], v[146:147], v[198:199], v[174:175]
	v_pk_add_f32 v[174:175], v[150:151], v[174:175]
	v_mul_f32_e32 v178, 0xbfb8aa3b, v174
	v_mul_f32_e32 v179, 0xbfb8aa3b, v175
	v_exp_f32_e32 v178, v178
	v_exp_f32_e32 v179, v179
	v_add_f32_e32 v178, 1.0, v178
	v_add_f32_e32 v179, 1.0, v179
	v_rcp_f32_e32 v178, v178
	v_rcp_f32_e32 v179, v179
	v_mov_b32_dpp v183, v195 row_ror:1 row_mask:0xf bank_mask:0xf
	v_pk_mul_f32 v[174:175], v[174:175], v[178:179]
	v_cvt_pk_bf16_f32 v178, v172, v173
	v_or_b32_e32 v172, s90, v209
	v_pk_mul_f32 v[174:175], v[180:181], v[174:175]
	v_mad_i64_i32 v[170:171], s[46:47], v172, s0, v[170:171]
	v_cvt_pk_bf16_f32 v179, v174, v175
	v_lshl_add_u64 v[172:173], v[170:171], 0, v[176:177]
	global_store_dwordx2 v[172:173], v[178:179], off
	v_cndmask_b32_e64 v170, v100, v108, s[6:7]
	v_cndmask_b32_e64 v171, v102, v110, s[6:7]
	s_nop 0
	v_mov_b32_dpp v178, v170 row_ror:1 row_mask:0xf bank_mask:0xf
	v_cndmask_b32_e64 v170, v68, v76, s[6:7]
	v_cndmask_b32_e64 v175, v103, v111, s[6:7]
	s_nop 0
	v_mov_b32_dpp v196, v170 row_ror:1 row_mask:0xf bank_mask:0xf
	v_cndmask_b32_e64 v170, v101, v109, s[6:7]
	s_nop 1
	v_mov_b32_dpp v179, v170 row_ror:1 row_mask:0xf bank_mask:0xf
	v_cndmask_b32_e64 v170, v69, v77, s[6:7]
	s_movk_i32 s40, 0x2c00
	v_mov_b32_dpp v180, v100 row_ror:15 row_mask:0xf bank_mask:0xf
	v_mov_b32_dpp v197, v170 row_ror:1 row_mask:0xf bank_mask:0xf
	v_mov_b32_dpp v198, v68 row_ror:15 row_mask:0xf bank_mask:0xf
	v_mov_b32_dpp v181, v101 row_ror:15 row_mask:0xf bank_mask:0xf
	v_mov_b32_dpp v170, v171 row_ror:1 row_mask:0xf bank_mask:0xf
	v_cndmask_b32_e64 v171, v70, v78, s[6:7]
	v_mov_b32_dpp v199, v69 row_ror:15 row_mask:0xf bank_mask:0xf
	v_mov_b32_dpp v174, v102 row_ror:15 row_mask:0xf bank_mask:0xf
	v_mov_b32_dpp v182, v171 row_ror:1 row_mask:0xf bank_mask:0xf
	v_mov_b32_dpp v194, v70 row_ror:15 row_mask:0xf bank_mask:0xf
	v_mov_b32_dpp v195, v71 row_ror:15 row_mask:0xf bank_mask:0xf
	v_mov_b32_dpp v171, v175 row_ror:1 row_mask:0xf bank_mask:0xf
	v_or_b32_e32 v217, s90, v210
	s_nop 0
	v_mov_b32_dpp v175, v103 row_ror:15 row_mask:0xf bank_mask:0xf
	s_and_saveexec_b64 vcc, s[8:9]
	v_readlane_b32 s62, v254, 14
	s_movk_i32 s63, 0x7fff
	s_cbranch_execz .LBB0_119
	v_pk_mul_f32 v[218:219], v[68:69], v[152:153]
	v_pk_mul_f32 v[202:203], v[100:101], v[156:157]
	v_pk_fma_f32 v[196:197], v[140:141], v[196:197], v[218:219]
	v_pk_fma_f32 v[178:179], v[128:129], v[178:179], v[202:203]
	v_pk_fma_f32 v[196:197], v[144:145], v[198:199], v[196:197]
	v_pk_fma_f32 v[178:179], v[132:133], v[180:181], v[178:179]
	v_pk_add_f32 v[196:197], v[148:149], v[196:197]
	v_pk_add_f32 v[178:179], v[136:137], v[178:179]
	v_mul_f32_e32 v198, 0xbfb8aa3b, v196
	v_exp_f32_e32 v218, v198
	v_mul_f32_e32 v198, 0xbfb8aa3b, v197
	v_exp_f32_e32 v219, v198
	v_pk_mul_f32 v[198:199], v[70:71], v[154:155]
	v_add_f32_e32 v218, 1.0, v218
	v_pk_fma_f32 v[182:183], v[142:143], v[182:183], v[198:199]
	v_add_f32_e32 v219, 1.0, v219
	v_pk_fma_f32 v[182:183], v[146:147], v[194:195], v[182:183]
	v_rcp_f32_e32 v218, v218
	v_pk_add_f32 v[182:183], v[150:151], v[182:183]
	v_rcp_f32_e32 v219, v219
	v_mul_f32_e32 v194, 0xbfb8aa3b, v182
	v_mul_f32_e32 v195, 0xbfb8aa3b, v183
	v_exp_f32_e32 v194, v194
	v_exp_f32_e32 v195, v195
	v_pk_mul_f32 v[180:181], v[196:197], v[218:219]
	v_pk_mul_f32 v[200:201], v[102:103], v[158:159]
	v_pk_mul_f32 v[178:179], v[178:179], v[180:181]
	v_add_f32_e32 v180, 1.0, v194
	v_add_f32_e32 v181, 1.0, v195
	v_rcp_f32_e32 v180, v180
	v_rcp_f32_e32 v181, v181
	v_pk_fma_f32 v[170:171], v[130:131], v[170:171], v[200:201]
	v_readlane_b32 s46, v254, 39
	v_pk_fma_f32 v[170:171], v[134:135], v[174:175], v[170:171]
	v_pk_mul_f32 v[174:175], v[182:183], v[180:181]
	v_pk_add_f32 v[170:171], v[138:139], v[170:171]
	v_readlane_b32 s47, v254, 40
	v_pk_mul_f32 v[170:171], v[170:171], v[174:175]
	v_cvt_pk_bf16_f32 v174, v178, v179
	v_cvt_pk_bf16_f32 v175, v170, v171
	v_mov_b64_e32 v[170:171], s[46:47]
	v_mad_i64_i32 v[170:171], s[46:47], v217, s40, v[170:171]
	v_lshl_add_u64 v[170:171], v[162:163], 1, v[170:171]
	global_store_dwordx2 v[170:171], v[174:175], off

; DI unsigned pk2(float lo, float hi) { f32x2 v = {lo, hi}; return __builtin_bit_cast(unsigned, __builtin_convertvector(v, bf16x2v)); }
; DI float dpp_ror1(float v) { return __builtin_bit_cast(float, __builtin_amdgcn_update_dpp(0, __builtin_bit_cast(int, v), 0x121, 0xF, 0xF, false)); }
; DI float dpp_rol1(float v) { return __builtin_bit_cast(float, __builtin_amdgcn_update_dpp(0, __builtin_bit_cast(int, v), 0x12F, 0xF, 0xF, false)); }
;     DI void operator()(const f32x4 (&acc)[2][2][4][2], const Unit& u, int wr, int wc, int fr, int fq) const {
;     ...
;                 for (int m = 0; m < 4; ++m) {
;                     const int rho = 16 * m + fr;
;                     const f32x4 ca_ = acc[ai][0][m][n], cg_ = acc[ai][1][m][n];
;                     const f32x4 ua_ = acc[ai][0][m > 0 ? m - 1 : 0][n], ug_ = acc[ai][1][m > 0 ? m - 1 : 0][n];
;                     const f32x4 da_ = acc[ai][0][m < 3 ? m + 1 : 3][n], dg_ = acc[ai][1][m < 3 ? m + 1 : 3][n];
;                     float o[4];
; #pragma unroll
;                     for (int j = 0; j < 4; ++j) {
;                         const float upa = dpp_ror1(fr == 15 ? ua_[j] : ca_[j]), dna = dpp_rol1(fr == 0 ? da_[j] : ca_[j]);
;                         const float upg = dpp_ror1(fr == 15 ? ug_[j] : cg_[j]), dng = dpp_rol1(fr == 0 ? dg_[j] : cg_[j]);
;                         const float va = wa0[j] * upa + wa1[j] * ca_[j] + wa2[j] * dna + ba[j];
;                         const float vg = wg0[j] * upg + wg1[j] * cg_[j] + wg2[j] * dng + bg[j];
;                         const float sgm = vg * __builtin_amdgcn_rcpf(1.f + __builtin_amdgcn_exp2f(-vg * LOG2E));
;                         o[j] = sgm * va;
;                     }
;                     if (rho >= 1 && rho <= 62) { u32x2 w; w.x = pk2(o[0], o[1]); w.y = pk2(o[2], o[3]); *(u32x2*)(ACT + (size_t)(row0 + rho) * DFF + ca) = w; }
.LBB0_121:
	s_or_b64 exec, exec, s[56:57]
	v_cndmask_b32_e64 v174, v60, v52, s[10:11]
	s_nop 1
	v_mov_b32_dpp v182, v174 row_ror:15 row_mask:0xf bank_mask:0xf
	v_cndmask_b32_e64 v174, v28, v20, s[10:11]
	v_cndmask_b32_e64 v175, v62, v54, s[10:11]
	s_nop 0
	v_mov_b32_dpp v200, v174 row_ror:15 row_mask:0xf bank_mask:0xf
	v_cndmask_b32_e64 v174, v61, v53, s[10:11]
	s_add_i32 s54, s54, 2
	s_nop 0
	v_mov_b32_dpp v183, v174 row_ror:15 row_mask:0xf bank_mask:0xf
	v_cndmask_b32_e64 v174, v29, v21, s[10:11]
	v_mov_b32_dpp v178, v175 row_ror:15 row_mask:0xf bank_mask:0xf
	v_cndmask_b32_e64 v175, v30, v22, s[10:11]
	v_cndmask_b32_e64 v195, v63, v55, s[10:11]
	s_lshl_b32 s44, s54, 6
	v_mov_b32_dpp v201, v174 row_ror:15 row_mask:0xf bank_mask:0xf
	v_mov_b32_dpp v196, v175 row_ror:15 row_mask:0xf bank_mask:0xf
	v_mov_b32_dpp v179, v195 row_ror:15 row_mask:0xf bank_mask:0xf
	v_cndmask_b32_e64 v202, v31, v23, s[10:11]
	v_mov_b32_dpp v180, v60 row_ror:1 row_mask:0xf bank_mask:0xf
	v_mov_b32_dpp v198, v28 row_ror:1 row_mask:0xf bank_mask:0xf
	v_mov_b32_dpp v181, v61 row_ror:1 row_mask:0xf bank_mask:0xf
	v_mov_b32_dpp v199, v29 row_ror:1 row_mask:0xf bank_mask:0xf
	v_mov_b32_dpp v174, v62 row_ror:1 row_mask:0xf bank_mask:0xf
	v_mov_b32_dpp v194, v30 row_ror:1 row_mask:0xf bank_mask:0xf
	v_mov_b32_dpp v175, v63 row_ror:1 row_mask:0xf bank_mask:0xf
	v_mov_b32_dpp v195, v31 row_ror:1 row_mask:0xf bank_mask:0xf
	v_mov_b32_dpp v197, v202 row_ror:15 row_mask:0xf bank_mask:0xf
	v_or_b32_e32 v218, s44, v160
	s_and_saveexec_b64 vcc, s[12:13]
	s_cbranch_execz .LBB0_123
	v_pk_mul_f32 v[222:223], v[28:29], v[152:153]
	v_pk_mul_f32 v[220:221], v[60:61], v[156:157]
	v_pk_fma_f32 v[198:199], v[140:141], v[198:199], v[222:223]
	v_pk_fma_f32 v[180:181], v[128:129], v[180:181], v[220:221]
	v_pk_fma_f32 v[198:199], v[144:145], v[200:201], v[198:199]
	v_pk_fma_f32 v[180:181], v[132:133], v[182:183], v[180:181]
	v_pk_add_f32 v[198:199], v[148:149], v[198:199]
	v_pk_add_f32 v[180:181], v[136:137], v[180:181]
	v_mul_f32_e32 v200, 0xbfb8aa3b, v198
	v_exp_f32_e32 v219, v200
	v_mul_f32_e32 v200, 0xbfb8aa3b, v199
	v_exp_f32_e32 v223, v200
	v_pk_mul_f32 v[200:201], v[30:31], v[154:155]
	v_add_f32_e32 v219, 1.0, v219
	v_pk_fma_f32 v[194:195], v[142:143], v[194:195], v[200:201]
	v_rcp_f32_e32 v222, v219
	v_pk_fma_f32 v[194:195], v[146:147], v[196:197], v[194:195]
	v_add_f32_e32 v219, 1.0, v223
	v_pk_add_f32 v[194:195], v[150:151], v[194:195]
	v_rcp_f32_e32 v223, v219
	v_mul_f32_e32 v196, 0xbfb8aa3b, v194
	v_mul_f32_e32 v197, 0xbfb8aa3b, v195
	v_exp_f32_e32 v196, v196
	v_exp_f32_e32 v197, v197
	v_pk_mul_f32 v[182:183], v[198:199], v[222:223]
	v_pk_mul_f32 v[202:203], v[62:63], v[158:159]
	v_pk_mul_f32 v[180:181], v[180:181], v[182:183]
	v_add_f32_e32 v182, 1.0, v196
	v_add_f32_e32 v183, 1.0, v197
	v_rcp_f32_e32 v182, v182
	v_rcp_f32_e32 v183, v183
	v_pk_fma_f32 v[174:175], v[130:131], v[174:175], v[202:203]
	v_readlane_b32 s46, v254, 39
	v_pk_fma_f32 v[174:175], v[134:135], v[178:179], v[174:175]
	v_pk_mul_f32 v[178:179], v[194:195], v[182:183]
	v_pk_add_f32 v[174:175], v[138:139], v[174:175]
	v_readlane_b32 s47, v254, 40
	v_pk_mul_f32 v[174:175], v[174:175], v[178:179]
	v_cvt_pk_bf16_f32 v178, v180, v181
	v_cvt_pk_bf16_f32 v179, v174, v175
	v_mov_b64_e32 v[174:175], s[46:47]
	v_mad_i64_i32 v[174:175], s[46:47], v218, s40, v[174:175]
	v_lshl_add_u64 v[174:175], v[162:163], 1, v[174:175]
	global_store_dwordx2 v[174:175], v[178:179], off

; DI unsigned pk2(float lo, float hi) { f32x2 v = {lo, hi}; return __builtin_bit_cast(unsigned, __builtin_convertvector(v, bf16x2v)); }
; DI float dpp_ror1(float v) { return __builtin_bit_cast(float, __builtin_amdgcn_update_dpp(0, __builtin_bit_cast(int, v), 0x121, 0xF, 0xF, false)); }
; DI float dpp_rol1(float v) { return __builtin_bit_cast(float, __builtin_amdgcn_update_dpp(0, __builtin_bit_cast(int, v), 0x12F, 0xF, 0xF, false)); }
;     DI void operator()(const f32x4 (&acc)[2][2][4][2], const Unit& u, int wr, int wc, int fr, int fq) const {
;     ...
;                 for (int m = 0; m < 4; ++m) {
;                     const int rho = 16 * m + fr;
;                     const f32x4 ca_ = acc[ai][0][m][n], cg_ = acc[ai][1][m][n];
;                     const f32x4 ua_ = acc[ai][0][m > 0 ? m - 1 : 0][n], ug_ = acc[ai][1][m > 0 ? m - 1 : 0][n];
;                     const f32x4 da_ = acc[ai][0][m < 3 ? m + 1 : 3][n], dg_ = acc[ai][1][m < 3 ? m + 1 : 3][n];
;                     float o[4];
; #pragma unroll
;                     for (int j = 0; j < 4; ++j) {
;                         const float upa = dpp_ror1(fr == 15 ? ua_[j] : ca_[j]), dna = dpp_rol1(fr == 0 ? da_[j] : ca_[j]);
;                         const float upg = dpp_ror1(fr == 15 ? ug_[j] : cg_[j]), dng = dpp_rol1(fr == 0 ? dg_[j] : cg_[j]);
;                         const float va = wa0[j] * upa + wa1[j] * ca_[j] + wa2[j] * dna + ba[j];
;                         const float vg = wg0[j] * upg + wg1[j] * cg_[j] + wg2[j] * dng + bg[j];
;                         const float sgm = vg * __builtin_amdgcn_rcpf(1.f + __builtin_amdgcn_exp2f(-vg * LOG2E));
;                         o[j] = sgm * va;
;                     }
;                     if (rho >= 1 && rho <= 62) { u32x2 w; w.x = pk2(o[0], o[1]); w.y = pk2(o[2], o[3]); *(u32x2*)(ACT + (size_t)(row0 + rho) * DFF + ca) = w; }
.LBB0_125:
	s_or_b64 exec, exec, s[56:57]
	v_cndmask_b32_e64 v175, v52, v60, s[6:7]
	s_nop 1
	v_mov_b32_dpp v174, v175 row_ror:1 row_mask:0xf bank_mask:0xf
	v_cndmask_b32_e64 v175, v52, v44, s[10:11]
	v_cndmask_b32_e64 v179, v53, v61, s[6:7]
	s_nop 0
	v_mov_b32_dpp v178, v175 row_ror:15 row_mask:0xf bank_mask:0xf
	v_cndmask_b32_e64 v175, v20, v28, s[6:7]
	v_cndmask_b32_e64 v181, v53, v45, s[10:11]
	v_cndmask_b32_e64 v183, v21, v29, s[6:7]
	v_mov_b32_dpp v180, v175 row_ror:1 row_mask:0xf bank_mask:0xf
	v_cndmask_b32_e64 v175, v20, v12, s[10:11]
	v_cndmask_b32_e64 v194, v21, v13, s[10:11]
	v_pk_mul_f32 v[224:225], v[20:21], v[152:153]
	v_mov_b32_dpp v182, v175 row_ror:15 row_mask:0xf bank_mask:0xf
	v_pk_mul_f32 v[220:221], v[52:53], v[156:157]
	v_cndmask_b32_e64 v195, v54, v62, s[6:7]
	v_mov_b32_dpp v175, v179 row_ror:1 row_mask:0xf bank_mask:0xf
	v_pk_fma_f32 v[174:175], v[128:129], v[174:175], v[220:221]
	v_mov_b32_dpp v179, v181 row_ror:15 row_mask:0xf bank_mask:0xf
	v_pk_fma_f32 v[174:175], v[132:133], v[178:179], v[174:175]
	v_mov_b32_dpp v181, v183 row_ror:1 row_mask:0xf bank_mask:0xf
	v_pk_fma_f32 v[180:181], v[140:141], v[180:181], v[224:225]
	v_mov_b32_dpp v183, v194 row_ror:15 row_mask:0xf bank_mask:0xf
	v_pk_fma_f32 v[180:181], v[144:145], v[182:183], v[180:181]
	v_pk_add_f32 v[180:181], v[148:149], v[180:181]
	v_cndmask_b32_e64 v197, v55, v63, s[6:7]
	v_mul_f32_e32 v182, 0xbfb8aa3b, v180
	v_mul_f32_e32 v178, 0xbfb8aa3b, v181
	v_exp_f32_e32 v182, v182
	v_exp_f32_e32 v178, v178
	v_mov_b32_dpp v194, v195 row_ror:1 row_mask:0xf bank_mask:0xf
	v_cndmask_b32_e64 v195, v54, v46, s[10:11]
	v_add_f32_e32 v182, 1.0, v182
	v_add_f32_e32 v178, 1.0, v178
	v_mov_b32_dpp v196, v195 row_ror:15 row_mask:0xf bank_mask:0xf
	v_cndmask_b32_e64 v195, v22, v30, s[6:7]
	v_rcp_f32_e32 v182, v182
	v_rcp_f32_e32 v183, v178
	v_mov_b32_dpp v198, v195 row_ror:1 row_mask:0xf bank_mask:0xf
	v_cndmask_b32_e64 v195, v22, v14, s[10:11]
	v_cndmask_b32_e64 v199, v55, v47, s[10:11]
	v_cndmask_b32_e64 v201, v23, v31, s[6:7]
	v_mov_b32_dpp v200, v195 row_ror:15 row_mask:0xf bank_mask:0xf
	v_cndmask_b32_e64 v202, v23, v15, s[10:11]
	v_pk_mul_f32 v[222:223], v[22:23], v[154:155]
	v_mov_b32_dpp v195, v197 row_ror:1 row_mask:0xf bank_mask:0xf
	v_pk_add_f32 v[174:175], v[136:137], v[174:175]
	v_pk_mul_f32 v[178:179], v[180:181], v[182:183]
	v_mov_b32_dpp v197, v199 row_ror:15 row_mask:0xf bank_mask:0xf
	v_pk_mul_f32 v[174:175], v[174:175], v[178:179]
	v_readlane_b32 s46, v254, 39
	v_mov_b32_dpp v199, v201 row_ror:1 row_mask:0xf bank_mask:0xf
	v_pk_fma_f32 v[178:179], v[142:143], v[198:199], v[222:223]
	v_readlane_b32 s47, v254, 40
	v_mov_b32_dpp v201, v202 row_ror:15 row_mask:0xf bank_mask:0xf
	v_pk_fma_f32 v[178:179], v[146:147], v[200:201], v[178:179]
	v_pk_mul_f32 v[202:203], v[54:55], v[158:159]
	v_pk_add_f32 v[178:179], v[150:151], v[178:179]
	v_pk_fma_f32 v[182:183], v[130:131], v[194:195], v[202:203]
	v_mul_f32_e32 v180, 0xbfb8aa3b, v178
	v_mul_f32_e32 v181, 0xbfb8aa3b, v179
	v_exp_f32_e32 v180, v180
	v_exp_f32_e32 v181, v181
	v_pk_fma_f32 v[182:183], v[134:135], v[196:197], v[182:183]
	s_movk_i32 s0, 0x2c00
	v_add_f32_e32 v180, 1.0, v180
	v_add_f32_e32 v181, 1.0, v181
	v_rcp_f32_e32 v180, v180
	v_rcp_f32_e32 v181, v181
	v_pk_add_f32 v[182:183], v[138:139], v[182:183]
	v_pk_mul_f32 v[178:179], v[178:179], v[180:181]
	v_cvt_pk_bf16_f32 v180, v174, v175
	v_pk_mul_f32 v[178:179], v[182:183], v[178:179]
	v_or_b32_e32 v174, s44, v208
	v_cvt_pk_bf16_f32 v181, v178, v179
	v_mov_b64_e32 v[178:179], s[46:47]
	v_mad_i64_i32 v[174:175], s[46:47], v174, s0, v[178:179]
	v_lshl_add_u64 v[174:175], v[174:175], 0, v[176:177]
	global_store_dwordx2 v[174:175], v[180:181], off
	v_cndmask_b32_e64 v181, v44, v52, s[6:7]
	v_cndmask_b32_e64 v183, v45, v53, s[6:7]
	s_nop 0
	v_mov_b32_dpp v180, v181 row_ror:1 row_mask:0xf bank_mask:0xf
	v_cndmask_b32_e64 v181, v44, v36, s[10:11]
	v_cndmask_b32_e64 v195, v45, v37, s[10:11]
	v_cndmask_b32_e64 v197, v13, v21, s[6:7]
	v_mov_b32_dpp v182, v181 row_ror:15 row_mask:0xf bank_mask:0xf
	v_cndmask_b32_e64 v181, v12, v20, s[6:7]
	v_cndmask_b32_e64 v198, v13, v5, s[10:11]
	v_pk_mul_f32 v[224:225], v[12:13], v[152:153]
	v_mov_b32_dpp v194, v181 row_ror:1 row_mask:0xf bank_mask:0xf
	v_cndmask_b32_e64 v181, v12, v4, s[10:11]
	v_pk_mul_f32 v[234:235], v[44:45], v[156:157]
	v_cndmask_b32_e64 v199, v46, v54, s[6:7]
	v_mov_b32_dpp v196, v181 row_ror:15 row_mask:0xf bank_mask:0xf
	v_mov_b32_dpp v181, v183 row_ror:1 row_mask:0xf bank_mask:0xf
	v_pk_fma_f32 v[180:181], v[128:129], v[180:181], v[234:235]
	v_mov_b32_dpp v183, v195 row_ror:15 row_mask:0xf bank_mask:0xf
	v_pk_fma_f32 v[180:181], v[132:133], v[182:183], v[180:181]
	v_cndmask_b32_e64 v201, v47, v55, s[6:7]
	v_mov_b32_dpp v195, v197 row_ror:1 row_mask:0xf bank_mask:0xf
	v_pk_fma_f32 v[194:195], v[140:141], v[194:195], v[224:225]
	v_cndmask_b32_e64 v203, v47, v39, s[10:11]
	v_mov_b32_dpp v197, v198 row_ror:15 row_mask:0xf bank_mask:0xf
	v_pk_fma_f32 v[194:195], v[144:145], v[196:197], v[194:195]
	v_pk_add_f32 v[194:195], v[148:149], v[194:195]
	v_cndmask_b32_e64 v221, v15, v23, s[6:7]
	v_mul_f32_e32 v196, 0xbfb8aa3b, v194
	v_mul_f32_e32 v182, 0xbfb8aa3b, v195
	v_exp_f32_e32 v196, v196
	v_exp_f32_e32 v182, v182
	v_mov_b32_dpp v198, v199 row_ror:1 row_mask:0xf bank_mask:0xf
; DI unsigned pk2(float lo, float hi) { f32x2 v = {lo, hi}; return __builtin_bit_cast(unsigned, __builtin_convertvector(v, bf16x2v)); }
; DI float dpp_ror1(float v) { return __builtin_bit_cast(float, __builtin_amdgcn_update_dpp(0, __builtin_bit_cast(int, v), 0x121, 0xF, 0xF, false)); }
; DI float dpp_rol1(float v) { return __builtin_bit_cast(float, __builtin_amdgcn_update_dpp(0, __builtin_bit_cast(int, v), 0x12F, 0xF, 0xF, false)); }
;     DI void operator()(const f32x4 (&acc)[2][2][4][2], const Unit& u, int wr, int wc, int fr, int fq) const {
;     ...
;                 for (int m = 0; m < 4; ++m) {
;                     const int rho = 16 * m + fr;
;                     const f32x4 ca_ = acc[ai][0][m][n], cg_ = acc[ai][1][m][n];
;                     const f32x4 ua_ = acc[ai][0][m > 0 ? m - 1 : 0][n], ug_ = acc[ai][1][m > 0 ? m - 1 : 0][n];
;                     const f32x4 da_ = acc[ai][0][m < 3 ? m + 1 : 3][n], dg_ = acc[ai][1][m < 3 ? m + 1 : 3][n];
;                     float o[4];
; #pragma unroll
;                     for (int j = 0; j < 4; ++j) {
;                         const float upa = dpp_ror1(fr == 15 ? ua_[j] : ca_[j]), dna = dpp_rol1(fr == 0 ? da_[j] : ca_[j]);
;                         const float upg = dpp_ror1(fr == 15 ? ug_[j] : cg_[j]), dng = dpp_rol1(fr == 0 ? dg_[j] : cg_[j]);
;                         const float va = wa0[j] * upa + wa1[j] * ca_[j] + wa2[j] * dna + ba[j];
;                         const float vg = wg0[j] * upg + wg1[j] * cg_[j] + wg2[j] * dng + bg[j];
;                         const float sgm = vg * __builtin_amdgcn_rcpf(1.f + __builtin_amdgcn_exp2f(-vg * LOG2E));
;                         o[j] = sgm * va;
;                     }
;                     if (rho >= 1 && rho <= 62) { u32x2 w; w.x = pk2(o[0], o[1]); w.y = pk2(o[2], o[3]); *(u32x2*)(ACT + (size_t)(row0 + rho) * DFF + ca) = w; }
	v_cndmask_b32_e64 v199, v46, v38, s[10:11]
	v_add_f32_e32 v196, 1.0, v196
	v_add_f32_e32 v182, 1.0, v182
	v_mov_b32_dpp v200, v199 row_ror:15 row_mask:0xf bank_mask:0xf
	v_cndmask_b32_e64 v199, v14, v22, s[6:7]
	v_rcp_f32_e32 v196, v196
	v_rcp_f32_e32 v197, v182
	v_mov_b32_dpp v202, v199 row_ror:1 row_mask:0xf bank_mask:0xf
	v_cndmask_b32_e64 v199, v14, v6, s[10:11]
	v_cndmask_b32_e64 v222, v15, v7, s[10:11]
	v_pk_add_f32 v[180:181], v[136:137], v[180:181]
	v_mov_b32_dpp v220, v199 row_ror:15 row_mask:0xf bank_mask:0xf
	v_pk_mul_f32 v[182:183], v[194:195], v[196:197]
	v_pk_mul_f32 v[224:225], v[46:47], v[158:159]
	v_mov_b32_dpp v199, v201 row_ror:1 row_mask:0xf bank_mask:0xf
	v_pk_mul_f32 v[180:181], v[180:181], v[182:183]
	v_pk_fma_f32 v[196:197], v[130:131], v[198:199], v[224:225]
	v_mov_b32_dpp v201, v203 row_ror:15 row_mask:0xf bank_mask:0xf
	v_pk_fma_f32 v[196:197], v[134:135], v[200:201], v[196:197]
	v_cvt_pk_bf16_f32 v180, v180, v181
	v_mov_b32_dpp v203, v221 row_ror:1 row_mask:0xf bank_mask:0xf
	v_pk_add_f32 v[196:197], v[138:139], v[196:197]
	v_mov_b32_dpp v221, v222 row_ror:15 row_mask:0xf bank_mask:0xf
	v_pk_mul_f32 v[222:223], v[14:15], v[154:155]
	v_pk_fma_f32 v[182:183], v[142:143], v[202:203], v[222:223]
	v_cndmask_b32_e64 v199, v7, v15, s[6:7]
	v_pk_fma_f32 v[182:183], v[146:147], v[220:221], v[182:183]
	v_pk_add_f32 v[182:183], v[150:151], v[182:183]
	v_mul_f32_e32 v194, 0xbfb8aa3b, v182
	v_mul_f32_e32 v195, 0xbfb8aa3b, v183
	v_exp_f32_e32 v194, v194
	v_exp_f32_e32 v195, v195
	v_mov_b32_dpp v202, v4 row_ror:15 row_mask:0xf bank_mask:0xf
	v_add_f32_e32 v194, 1.0, v194
	v_add_f32_e32 v195, 1.0, v195
	v_rcp_f32_e32 v194, v194
	v_rcp_f32_e32 v195, v195
	v_mov_b32_dpp v203, v5 row_ror:15 row_mask:0xf bank_mask:0xf
	v_mov_b32_dpp v198, v6 row_ror:15 row_mask:0xf bank_mask:0xf
	v_or_b32_e32 v220, s44, v210
	v_pk_mul_f32 v[182:183], v[182:183], v[194:195]
	v_pk_mul_f32 v[182:183], v[196:197], v[182:183]
	v_cvt_pk_bf16_f32 v181, v182, v183
	v_or_b32_e32 v182, s44, v209
	v_mad_i64_i32 v[178:179], s[46:47], v182, s0, v[178:179]
	v_lshl_add_u64 v[178:179], v[178:179], 0, v[176:177]
	v_cndmask_b32_e64 v176, v36, v44, s[6:7]
	v_cndmask_b32_e64 v177, v38, v46, s[6:7]
	s_nop 0
	v_mov_b32_dpp v182, v176 row_ror:1 row_mask:0xf bank_mask:0xf
	v_cndmask_b32_e64 v176, v4, v12, s[6:7]
	global_store_dwordx2 v[178:179], v[180:181], off
	v_cndmask_b32_e64 v181, v39, v47, s[6:7]
	v_mov_b32_dpp v200, v176 row_ror:1 row_mask:0xf bank_mask:0xf
	v_cndmask_b32_e64 v176, v37, v45, s[6:7]
	s_nop 1
	v_mov_b32_dpp v183, v176 row_ror:1 row_mask:0xf bank_mask:0xf
	v_cndmask_b32_e64 v176, v5, v13, s[6:7]
	v_mov_b32_dpp v197, v199 row_ror:1 row_mask:0xf bank_mask:0xf
	s_nop 0
	v_mov_b32_dpp v201, v176 row_ror:1 row_mask:0xf bank_mask:0xf
	v_mov_b32_dpp v194, v36 row_ror:15 row_mask:0xf bank_mask:0xf
	v_mov_b32_dpp v176, v177 row_ror:1 row_mask:0xf bank_mask:0xf
	v_cndmask_b32_e64 v177, v6, v14, s[6:7]
	v_mov_b32_dpp v195, v37 row_ror:15 row_mask:0xf bank_mask:0xf
	v_mov_b32_dpp v180, v38 row_ror:15 row_mask:0xf bank_mask:0xf
	v_mov_b32_dpp v196, v177 row_ror:1 row_mask:0xf bank_mask:0xf
	v_mov_b32_dpp v199, v7 row_ror:15 row_mask:0xf bank_mask:0xf
	s_nop 0
	v_mov_b32_dpp v177, v181 row_ror:1 row_mask:0xf bank_mask:0xf
	s_nop 1
	v_mov_b32_dpp v181, v39 row_ror:15 row_mask:0xf bank_mask:0xf
	s_and_saveexec_b64 vcc, s[8:9]
	s_cbranch_execz .LBB0_127
	v_pk_mul_f32 v[152:153], v[4:5], v[152:153]
	v_pk_mul_f32 v[156:157], v[36:37], v[156:157]
	v_pk_fma_f32 v[140:141], v[140:141], v[200:201], v[152:153]
	v_pk_fma_f32 v[128:129], v[128:129], v[182:183], v[156:157]
	v_pk_fma_f32 v[140:141], v[144:145], v[202:203], v[140:141]
	v_pk_fma_f32 v[128:129], v[132:133], v[194:195], v[128:129]
	v_pk_add_f32 v[140:141], v[148:149], v[140:141]
	v_pk_add_f32 v[128:129], v[136:137], v[128:129]
	v_mul_f32_e32 v144, 0xbfb8aa3b, v140
	v_exp_f32_e32 v148, v144
	v_mul_f32_e32 v144, 0xbfb8aa3b, v141
	v_exp_f32_e32 v149, v144
	v_pk_mul_f32 v[144:145], v[6:7], v[154:155]
	v_add_f32_e32 v148, 1.0, v148
	v_rcp_f32_e32 v148, v148
	v_add_f32_e32 v149, 1.0, v149
	v_rcp_f32_e32 v149, v149
	v_pk_fma_f32 v[136:137], v[142:143], v[196:197], v[144:145]
	v_pk_mul_f32 v[158:159], v[38:39], v[158:159]
	v_pk_fma_f32 v[136:137], v[146:147], v[198:199], v[136:137]
	v_pk_mul_f32 v[132:133], v[140:141], v[148:149]
	v_pk_add_f32 v[136:137], v[150:151], v[136:137]
	v_pk_mul_f32 v[128:129], v[128:129], v[132:133]
	v_mul_f32_e32 v140, 0xbfb8aa3b, v136
	v_mul_f32_e32 v141, 0xbfb8aa3b, v137
	v_exp_f32_e32 v140, v140
	v_exp_f32_e32 v141, v141
	v_pk_fma_f32 v[130:131], v[130:131], v[176:177], v[158:159]
	v_readlane_b32 s46, v254, 39
	v_add_f32_e32 v132, 1.0, v140
	v_add_f32_e32 v133, 1.0, v141
	v_rcp_f32_e32 v132, v132
	v_rcp_f32_e32 v133, v133
	v_pk_fma_f32 v[130:131], v[134:135], v[180:181], v[130:131]
	v_readlane_b32 s47, v254, 40
	v_pk_add_f32 v[130:131], v[138:139], v[130:131]
	v_pk_mul_f32 v[132:133], v[136:137], v[132:133]
	v_cvt_pk_bf16_f32 v128, v128, v129
	v_pk_mul_f32 v[130:131], v[130:131], v[132:133]
	s_nop 0
	v_cvt_pk_bf16_f32 v129, v130, v131
	v_mov_b64_e32 v[130:131], s[46:47]
	v_mad_i64_i32 v[130:131], s[46:47], v220, s0, v[130:131]
	v_lshl_add_u64 v[130:131], v[162:163], 1, v[130:131]
	global_store_dwordx2 v[130:131], v[128:129], off

; DI unsigned pk2(float lo, float hi) { f32x2 v = {lo, hi}; return __builtin_bit_cast(unsigned, __builtin_convertvector(v, bf16x2v)); }
; DI float dpp_ror1(float v) { return __builtin_bit_cast(float, __builtin_amdgcn_update_dpp(0, __builtin_bit_cast(int, v), 0x121, 0xF, 0xF, false)); }
;     DI void operator()(const f32x4 (&acc)[2][2][4][2], const Unit& u, int wr, int wc, int fr, int fq) const {
;     ...
;             const int ca = colA + 4 * n;
;             const f32x4 wa0 = *(const f32x4*)(cw + ca), wa1 = *(const f32x4*)(cw + DFF2 + ca), wa2 = *(const f32x4*)(cw + 2 * DFF2 + ca), ba = *(const f32x4*)(cb + ca);
;             const f32x4 wg0 = *(const f32x4*)(cw + DFF + ca), wg1 = *(const f32x4*)(cw + DFF2 + DFF + ca), wg2 = *(const f32x4*)(cw + 2 * DFF2 + DFF + ca), bg = *(const f32x4*)(cb + DFF + ca);
; #pragma unroll
;             for (int ai = 0; ai < 2; ++ai) {
;                 const int sg = 4 * u.pm + 2 * ai + wr, row0 = 64 * sg;
; #pragma unroll
;                 for (int m = 0; m < 4; ++m) {
;                     const int rho = 16 * m + fr;
;                     const f32x4 ca_ = acc[ai][0][m][n], cg_ = acc[ai][1][m][n];
;                     const f32x4 ua_ = acc[ai][0][m > 0 ? m - 1 : 0][n], ug_ = acc[ai][1][m > 0 ? m - 1 : 0][n];
;                     const f32x4 da_ = acc[ai][0][m < 3 ? m + 1 : 3][n], dg_ = acc[ai][1][m < 3 ? m + 1 : 3][n];
;                     float o[4];
; #pragma unroll
;                     for (int j = 0; j < 4; ++j) {
;                         const float upa = dpp_ror1(fr == 15 ? ua_[j] : ca_[j]), dna = dpp_rol1(fr == 0 ? da_[j] : ca_[j]);
;                         const float upg = dpp_ror1(fr == 15 ? ug_[j] : cg_[j]), dng = dpp_rol1(fr == 0 ? dg_[j] : cg_[j]);
;                         const float va = wa0[j] * upa + wa1[j] * ca_[j] + wa2[j] * dna + ba[j];
;                         const float vg = wg0[j] * upg + wg1[j] * cg_[j] + wg2[j] * dng + bg[j];
;                         const float sgm = vg * __builtin_amdgcn_rcpf(1.f + __builtin_amdgcn_exp2f(-vg * LOG2E));
;                         o[j] = sgm * va;
;                     }
;                     if (rho >= 1 && rho <= 62) { u32x2 w; w.x = pk2(o[0], o[1]); w.y = pk2(o[2], o[3]); *(u32x2*)(ACT + (size_t)(row0 + rho) * DFF + ca) = w; }
.LBB0_129:
	s_or_b64 exec, exec, s[56:57]
	v_or_b32_e32 v132, 4, v162
	v_ashrrev_i32_e32 v133, 31, v132
	v_lshlrev_b64 v[148:149], 2, v[132:133]
	v_lshl_add_u64 v[132:133], s[80:81], 0, v[148:149]
	v_lshl_add_u64 v[134:135], s[70:71], 0, v[148:149]
	v_lshl_add_u64 v[140:141], s[24:25], 0, v[148:149]
	v_lshl_add_u64 v[144:145], s[72:73], 0, v[148:149]
	ds_read_b128 v[128:131], v166 offset:16
	ds_read_b128 v[156:159], v166 offset:528
	s_nop 0
	ds_read_b128 v[132:135], v166 offset:1040
	s_nop 0
	ds_read_b128 v[136:139], v166 offset:1552
	s_nop 0
	ds_read_b128 v[140:143], v166 offset:2064
	s_nop 0
	ds_read_b128 v[152:155], v166 offset:2576
	v_lshl_add_u64 v[144:145], s[66:67], 0, v[148:149]
	v_lshl_add_u64 v[148:149], s[68:69], 0, v[148:149]
	ds_read_b128 v[144:147], v166 offset:3088
	v_cndmask_b32_e64 v164, v120, v112, s[10:11]
	ds_read_b128 v[148:151], v166 offset:3600
	s_nop 0
	v_mov_b32_dpp v182, v164 row_ror:15 row_mask:0xf bank_mask:0xf
	v_cndmask_b32_e64 v164, v88, v80, s[10:11]
	v_cndmask_b32_e64 v165, v122, v114, s[10:11]
	s_nop 0
	v_mov_b32_dpp v200, v164 row_ror:15 row_mask:0xf bank_mask:0xf
	v_cndmask_b32_e64 v164, v121, v113, s[10:11]
	v_mov_b32_dpp v166, v165 row_ror:15 row_mask:0xf bank_mask:0xf
	s_nop 0
	v_mov_b32_dpp v183, v164 row_ror:15 row_mask:0xf bank_mask:0xf
	v_cndmask_b32_e64 v164, v89, v81, s[10:11]
	v_cndmask_b32_e64 v165, v90, v82, s[10:11]
	v_cndmask_b32_e64 v195, v123, v115, s[10:11]
	v_mov_b32_dpp v201, v164 row_ror:15 row_mask:0xf bank_mask:0xf
	v_mov_b32_dpp v194, v165 row_ror:15 row_mask:0xf bank_mask:0xf
	v_mov_b32_dpp v167, v195 row_ror:15 row_mask:0xf bank_mask:0xf
	v_cndmask_b32_e64 v202, v91, v83, s[10:11]
	v_mov_b32_dpp v180, v120 row_ror:1 row_mask:0xf bank_mask:0xf
	v_mov_b32_dpp v198, v88 row_ror:1 row_mask:0xf bank_mask:0xf
	v_mov_b32_dpp v181, v121 row_ror:1 row_mask:0xf bank_mask:0xf
	v_mov_b32_dpp v199, v89 row_ror:1 row_mask:0xf bank_mask:0xf
	v_mov_b32_dpp v164, v122 row_ror:1 row_mask:0xf bank_mask:0xf
	v_mov_b32_dpp v196, v90 row_ror:1 row_mask:0xf bank_mask:0xf
	v_mov_b32_dpp v165, v123 row_ror:1 row_mask:0xf bank_mask:0xf
	v_mov_b32_dpp v197, v91 row_ror:1 row_mask:0xf bank_mask:0xf
	v_mov_b32_dpp v195, v202 row_ror:15 row_mask:0xf bank_mask:0xf
	s_and_saveexec_b64 vcc, s[12:13]
	s_cbranch_execz .LBB0_131
	s_waitcnt lgkmcnt(0)
	v_pk_mul_f32 v[224:225], v[88:89], v[152:153]
	v_pk_mul_f32 v[222:223], v[120:121], v[156:157]
	v_pk_fma_f32 v[198:199], v[140:141], v[198:199], v[224:225]
	v_pk_fma_f32 v[180:181], v[128:129], v[180:181], v[222:223]
	s_waitcnt lgkmcnt(0)
	v_pk_fma_f32 v[198:199], v[144:145], v[200:201], v[198:199]
	v_pk_fma_f32 v[180:181], v[132:133], v[182:183], v[180:181]
	s_waitcnt lgkmcnt(0)
	v_pk_add_f32 v[198:199], v[148:149], v[198:199]
	v_pk_add_f32 v[180:181], v[136:137], v[180:181]
	v_mul_f32_e32 v200, 0xbfb8aa3b, v198
	v_exp_f32_e32 v221, v200
	v_mul_f32_e32 v200, 0xbfb8aa3b, v199
	v_exp_f32_e32 v225, v200
	v_pk_mul_f32 v[200:201], v[90:91], v[154:155]
	v_add_f32_e32 v221, 1.0, v221
	v_pk_fma_f32 v[196:197], v[142:143], v[196:197], v[200:201]
	v_rcp_f32_e32 v224, v221
	v_pk_fma_f32 v[194:195], v[146:147], v[194:195], v[196:197]
	v_add_f32_e32 v221, 1.0, v225
	v_pk_add_f32 v[194:195], v[150:151], v[194:195]
	v_rcp_f32_e32 v225, v221
	v_mul_f32_e32 v196, 0xbfb8aa3b, v194
	v_mul_f32_e32 v197, 0xbfb8aa3b, v195
	v_exp_f32_e32 v196, v196
	v_exp_f32_e32 v197, v197
	v_pk_mul_f32 v[182:183], v[198:199], v[224:225]
	v_pk_mul_f32 v[202:203], v[122:123], v[158:159]
	v_pk_mul_f32 v[180:181], v[180:181], v[182:183]
	v_add_f32_e32 v182, 1.0, v196
	v_add_f32_e32 v183, 1.0, v197
	v_rcp_f32_e32 v182, v182
	v_rcp_f32_e32 v183, v183
	v_pk_fma_f32 v[164:165], v[130:131], v[164:165], v[202:203]
	v_readlane_b32 s46, v254, 39
	v_pk_fma_f32 v[164:165], v[134:135], v[166:167], v[164:165]
	v_pk_mul_f32 v[166:167], v[194:195], v[182:183]
	v_pk_add_f32 v[164:165], v[138:139], v[164:165]
	v_readlane_b32 s47, v254, 40
	v_pk_mul_f32 v[164:165], v[164:165], v[166:167]
	s_movk_i32 s0, 0x2c00
	v_cvt_pk_bf16_f32 v167, v164, v165
	v_mov_b64_e32 v[164:165], s[46:47]
	v_mad_i64_i32 v[164:165], s[46:47], v215, s0, v[164:165]
	v_cvt_pk_bf16_f32 v166, v180, v181
	v_lshl_add_u64 v[164:165], v[162:163], 1, v[164:165]
	global_store_dwordx2 v[164:165], v[166:167], off offset:8

; DI unsigned pk2(float lo, float hi) { f32x2 v = {lo, hi}; return __builtin_bit_cast(unsigned, __builtin_convertvector(v, bf16x2v)); }
; DI float dpp_ror1(float v) { return __builtin_bit_cast(float, __builtin_amdgcn_update_dpp(0, __builtin_bit_cast(int, v), 0x121, 0xF, 0xF, false)); }
; DI float dpp_rol1(float v) { return __builtin_bit_cast(float, __builtin_amdgcn_update_dpp(0, __builtin_bit_cast(int, v), 0x12F, 0xF, 0xF, false)); }
;     DI void operator()(const f32x4 (&acc)[2][2][4][2], const Unit& u, int wr, int wc, int fr, int fq) const {
;     ...
;                 for (int m = 0; m < 4; ++m) {
;                     const int rho = 16 * m + fr;
;                     const f32x4 ca_ = acc[ai][0][m][n], cg_ = acc[ai][1][m][n];
;                     const f32x4 ua_ = acc[ai][0][m > 0 ? m - 1 : 0][n], ug_ = acc[ai][1][m > 0 ? m - 1 : 0][n];
;                     const f32x4 da_ = acc[ai][0][m < 3 ? m + 1 : 3][n], dg_ = acc[ai][1][m < 3 ? m + 1 : 3][n];
;                     float o[4];
; #pragma unroll
;                     for (int j = 0; j < 4; ++j) {
;                         const float upa = dpp_ror1(fr == 15 ? ua_[j] : ca_[j]), dna = dpp_rol1(fr == 0 ? da_[j] : ca_[j]);
;                         const float upg = dpp_ror1(fr == 15 ? ug_[j] : cg_[j]), dng = dpp_rol1(fr == 0 ? dg_[j] : cg_[j]);
;                         const float va = wa0[j] * upa + wa1[j] * ca_[j] + wa2[j] * dna + ba[j];
;                         const float vg = wg0[j] * upg + wg1[j] * cg_[j] + wg2[j] * dng + bg[j];
;                         const float sgm = vg * __builtin_amdgcn_rcpf(1.f + __builtin_amdgcn_exp2f(-vg * LOG2E));
;                         o[j] = sgm * va;
;                     }
;                     if (rho >= 1 && rho <= 62) { u32x2 w; w.x = pk2(o[0], o[1]); w.y = pk2(o[2], o[3]); *(u32x2*)(ACT + (size_t)(row0 + rho) * DFF + ca) = w; }
.LBB0_133:
	s_or_b64 exec, exec, s[56:57]
	v_cndmask_b32_e64 v165, v112, v120, s[6:7]
	s_nop 1
	v_mov_b32_dpp v164, v165 row_ror:1 row_mask:0xf bank_mask:0xf
	v_cndmask_b32_e64 v165, v112, v104, s[10:11]
	v_cndmask_b32_e64 v167, v113, v121, s[6:7]
	s_nop 0
	v_mov_b32_dpp v166, v165 row_ror:15 row_mask:0xf bank_mask:0xf
	v_cndmask_b32_e64 v165, v80, v88, s[6:7]
	v_cndmask_b32_e64 v181, v113, v105, s[10:11]
	v_cndmask_b32_e64 v183, v81, v89, s[6:7]
	v_mov_b32_dpp v180, v165 row_ror:1 row_mask:0xf bank_mask:0xf
	v_cndmask_b32_e64 v165, v80, v72, s[10:11]
	v_cndmask_b32_e64 v194, v81, v73, s[10:11]
	s_waitcnt lgkmcnt(0)
	v_pk_mul_f32 v[224:225], v[80:81], v[152:153]
	v_mov_b32_dpp v182, v165 row_ror:15 row_mask:0xf bank_mask:0xf
	v_cndmask_b32_e64 v195, v114, v122, s[6:7]
	v_mov_b32_dpp v165, v167 row_ror:1 row_mask:0xf bank_mask:0xf
	v_mov_b32_dpp v167, v181 row_ror:15 row_mask:0xf bank_mask:0xf
	v_cndmask_b32_e64 v197, v115, v123, s[6:7]
	v_cndmask_b32_e64 v199, v115, v107, s[10:11]
	v_mov_b32_dpp v181, v183 row_ror:1 row_mask:0xf bank_mask:0xf
	v_pk_fma_f32 v[180:181], v[140:141], v[180:181], v[224:225]
	v_cndmask_b32_e64 v201, v83, v91, s[6:7]
	v_mov_b32_dpp v183, v194 row_ror:15 row_mask:0xf bank_mask:0xf
	s_waitcnt lgkmcnt(0)
	v_pk_fma_f32 v[180:181], v[144:145], v[182:183], v[180:181]
	s_waitcnt lgkmcnt(0)
	v_pk_add_f32 v[180:181], v[148:149], v[180:181]
	v_pk_mul_f32 v[222:223], v[112:113], v[156:157]
	v_mul_f32_e32 v182, 0xbfb8aa3b, v180
	v_exp_f32_e32 v215, v182
	v_mul_f32_e32 v182, 0xbfb8aa3b, v181
	v_exp_f32_e32 v216, v182
	v_mov_b32_dpp v194, v195 row_ror:1 row_mask:0xf bank_mask:0xf
	v_cndmask_b32_e64 v195, v114, v106, s[10:11]
	v_add_f32_e32 v215, 1.0, v215
	v_rcp_f32_e32 v224, v215
	v_mov_b32_dpp v196, v195 row_ror:15 row_mask:0xf bank_mask:0xf
	v_cndmask_b32_e64 v195, v82, v90, s[6:7]
	v_add_f32_e32 v215, 1.0, v216
	v_rcp_f32_e32 v225, v215
	v_mov_b32_dpp v198, v195 row_ror:1 row_mask:0xf bank_mask:0xf
	v_cndmask_b32_e64 v195, v82, v74, s[10:11]
	v_cndmask_b32_e64 v202, v83, v75, s[10:11]
	v_pk_mul_f32 v[182:183], v[82:83], v[154:155]
	v_mov_b32_dpp v200, v195 row_ror:15 row_mask:0xf bank_mask:0xf
	v_pk_fma_f32 v[164:165], v[128:129], v[164:165], v[222:223]
	v_pk_mul_f32 v[222:223], v[104:105], v[156:157]
	v_mov_b32_dpp v195, v197 row_ror:1 row_mask:0xf bank_mask:0xf
	v_pk_fma_f32 v[164:165], v[132:133], v[166:167], v[164:165]
	v_pk_mul_f32 v[166:167], v[180:181], v[224:225]
	v_mov_b32_dpp v197, v199 row_ror:15 row_mask:0xf bank_mask:0xf
	v_pk_add_f32 v[164:165], v[136:137], v[164:165]
	s_nop 0
	v_mov_b32_dpp v199, v201 row_ror:1 row_mask:0xf bank_mask:0xf
	v_pk_fma_f32 v[180:181], v[142:143], v[198:199], v[182:183]
	v_pk_mul_f32 v[164:165], v[164:165], v[166:167]
	v_mov_b32_dpp v201, v202 row_ror:15 row_mask:0xf bank_mask:0xf
	v_pk_fma_f32 v[180:181], v[146:147], v[200:201], v[180:181]
	v_pk_mul_f32 v[202:203], v[114:115], v[158:159]
	v_pk_add_f32 v[180:181], v[150:151], v[180:181]
	v_cvt_pk_bf16_f32 v164, v164, v165
	v_mul_f32_e32 v182, 0xbfb8aa3b, v180
	v_mul_f32_e32 v183, 0xbfb8aa3b, v181
	v_exp_f32_e32 v182, v182
	v_exp_f32_e32 v183, v183
	v_pk_mul_f32 v[200:201], v[72:73], v[152:153]
	v_add_f32_e32 v166, 1.0, v182
	v_add_f32_e32 v167, 1.0, v183
	v_rcp_f32_e32 v166, v166
	v_rcp_f32_e32 v167, v167
	v_pk_fma_f32 v[182:183], v[130:131], v[194:195], v[202:203]
	v_pk_fma_f32 v[182:183], v[134:135], v[196:197], v[182:183]
	v_pk_mul_f32 v[166:167], v[180:181], v[166:167]
	v_pk_add_f32 v[182:183], v[138:139], v[182:183]
	v_pk_mul_f32 v[166:167], v[182:183], v[166:167]
	v_cndmask_b32_e64 v181, v73, v81, s[6:7]
	v_cvt_pk_bf16_f32 v165, v166, v167
	global_store_dwordx2 v[168:169], v[164:165], off offset:8
	v_cndmask_b32_e64 v165, v104, v112, s[6:7]
	s_nop 1
	v_mov_b32_dpp v164, v165 row_ror:1 row_mask:0xf bank_mask:0xf
	v_cndmask_b32_e64 v165, v104, v96, s[10:11]
	v_cndmask_b32_e64 v167, v105, v113, s[6:7]
	v_cndmask_b32_e64 v169, v105, v97, s[10:11]
	v_mov_b32_dpp v166, v165 row_ror:15 row_mask:0xf bank_mask:0xf
	v_cndmask_b32_e64 v165, v72, v80, s[6:7]
	v_cndmask_b32_e64 v182, v73, v65, s[10:11]
	v_cndmask_b32_e64 v183, v106, v114, s[6:7]
	v_mov_b32_dpp v168, v165 row_ror:1 row_mask:0xf bank_mask:0xf
	v_cndmask_b32_e64 v165, v72, v64, s[10:11]
	v_cndmask_b32_e64 v195, v107, v115, s[6:7]
	s_nop 0
	v_mov_b32_dpp v180, v165 row_ror:15 row_mask:0xf bank_mask:0xf
	v_cndmask_b32_e64 v197, v107, v99, s[10:11]
	v_cndmask_b32_e64 v199, v75, v83, s[6:7]
	v_mov_b32_dpp v165, v167 row_ror:1 row_mask:0xf bank_mask:0xf
	v_cndmask_b32_e64 v202, v75, v67, s[10:11]
	v_pk_fma_f32 v[164:165], v[128:129], v[164:165], v[222:223]
	v_mov_b32_dpp v167, v169 row_ror:15 row_mask:0xf bank_mask:0xf
	v_pk_fma_f32 v[164:165], v[132:133], v[166:167], v[164:165]
	s_nop 0
	v_mov_b32_dpp v169, v181 row_ror:1 row_mask:0xf bank_mask:0xf
	v_pk_fma_f32 v[168:169], v[140:141], v[168:169], v[200:201]
	v_pk_add_f32 v[164:165], v[136:137], v[164:165]
	v_mov_b32_dpp v181, v182 row_ror:15 row_mask:0xf bank_mask:0xf
	v_pk_fma_f32 v[168:169], v[144:145], v[180:181], v[168:169]
	v_pk_add_f32 v[168:169], v[148:149], v[168:169]
	s_nop 0
	v_mul_f32_e32 v180, 0xbfb8aa3b, v168
	v_mul_f32_e32 v201, 0xbfb8aa3b, v169
	v_exp_f32_e32 v200, v180
; DI unsigned pk2(float lo, float hi) { f32x2 v = {lo, hi}; return __builtin_bit_cast(unsigned, __builtin_convertvector(v, bf16x2v)); }
; DI float dpp_ror1(float v) { return __builtin_bit_cast(float, __builtin_amdgcn_update_dpp(0, __builtin_bit_cast(int, v), 0x121, 0xF, 0xF, false)); }
; DI float dpp_rol1(float v) { return __builtin_bit_cast(float, __builtin_amdgcn_update_dpp(0, __builtin_bit_cast(int, v), 0x12F, 0xF, 0xF, false)); }
;     DI void operator()(const f32x4 (&acc)[2][2][4][2], const Unit& u, int wr, int wc, int fr, int fq) const {
;     ...
;                 for (int m = 0; m < 4; ++m) {
;                     const int rho = 16 * m + fr;
;                     const f32x4 ca_ = acc[ai][0][m][n], cg_ = acc[ai][1][m][n];
;                     const f32x4 ua_ = acc[ai][0][m > 0 ? m - 1 : 0][n], ug_ = acc[ai][1][m > 0 ? m - 1 : 0][n];
;                     const f32x4 da_ = acc[ai][0][m < 3 ? m + 1 : 3][n], dg_ = acc[ai][1][m < 3 ? m + 1 : 3][n];
;                     float o[4];
; #pragma unroll
;                     for (int j = 0; j < 4; ++j) {
;                         const float upa = dpp_ror1(fr == 15 ? ua_[j] : ca_[j]), dna = dpp_rol1(fr == 0 ? da_[j] : ca_[j]);
;                         const float upg = dpp_ror1(fr == 15 ? ug_[j] : cg_[j]), dng = dpp_rol1(fr == 0 ? dg_[j] : cg_[j]);
;                         const float va = wa0[j] * upa + wa1[j] * ca_[j] + wa2[j] * dna + ba[j];
;                         const float vg = wg0[j] * upg + wg1[j] * cg_[j] + wg2[j] * dng + bg[j];
;                         const float sgm = vg * __builtin_amdgcn_rcpf(1.f + __builtin_amdgcn_exp2f(-vg * LOG2E));
;                         o[j] = sgm * va;
;                     }
;                     if (rho >= 1 && rho <= 62) { u32x2 w; w.x = pk2(o[0], o[1]); w.y = pk2(o[2], o[3]); *(u32x2*)(ACT + (size_t)(row0 + rho) * DFF + ca) = w; }
	v_exp_f32_e32 v201, v201
	v_mov_b32_dpp v182, v183 row_ror:1 row_mask:0xf bank_mask:0xf
	v_cndmask_b32_e64 v183, v106, v98, s[10:11]
	v_add_f32_e32 v200, 1.0, v200
	v_add_f32_e32 v201, 1.0, v201
	v_mov_b32_dpp v194, v183 row_ror:15 row_mask:0xf bank_mask:0xf
	v_cndmask_b32_e64 v183, v74, v82, s[6:7]
	v_rcp_f32_e32 v200, v200
	v_rcp_f32_e32 v201, v201
	v_mov_b32_dpp v196, v183 row_ror:1 row_mask:0xf bank_mask:0xf
	v_cndmask_b32_e64 v183, v74, v66, s[10:11]
	v_pk_mul_f32 v[180:181], v[74:75], v[154:155]
	v_pk_mul_f32 v[166:167], v[168:169], v[200:201]
	v_mov_b32_dpp v198, v183 row_ror:15 row_mask:0xf bank_mask:0xf
	v_pk_mul_f32 v[164:165], v[164:165], v[166:167]
	s_nop 0
	v_mov_b32_dpp v183, v195 row_ror:1 row_mask:0xf bank_mask:0xf
	v_cvt_pk_bf16_f32 v164, v164, v165
	s_nop 0
	v_mov_b32_dpp v195, v197 row_ror:15 row_mask:0xf bank_mask:0xf
	s_nop 1
	v_mov_b32_dpp v197, v199 row_ror:1 row_mask:0xf bank_mask:0xf
	v_pk_fma_f32 v[168:169], v[142:143], v[196:197], v[180:181]
	v_mov_b32_dpp v199, v202 row_ror:15 row_mask:0xf bank_mask:0xf
	v_pk_fma_f32 v[168:169], v[146:147], v[198:199], v[168:169]
	v_pk_mul_f32 v[202:203], v[106:107], v[158:159]
	v_pk_add_f32 v[168:169], v[150:151], v[168:169]
	v_mul_f32_e32 v180, 0xbfb8aa3b, v168
	v_mul_f32_e32 v181, 0xbfb8aa3b, v169
	v_exp_f32_e32 v180, v180
	v_exp_f32_e32 v181, v181
	v_mov_b32_dpp v196, v64 row_ror:15 row_mask:0xf bank_mask:0xf
	v_mov_b32_dpp v197, v65 row_ror:15 row_mask:0xf bank_mask:0xf
	v_add_f32_e32 v166, 1.0, v180
	v_add_f32_e32 v167, 1.0, v181
	v_rcp_f32_e32 v166, v166
	v_rcp_f32_e32 v167, v167
	v_pk_fma_f32 v[180:181], v[130:131], v[182:183], v[202:203]
	v_cndmask_b32_e64 v183, v67, v75, s[6:7]
	v_pk_fma_f32 v[180:181], v[134:135], v[194:195], v[180:181]
	v_pk_mul_f32 v[166:167], v[168:169], v[166:167]
	v_pk_add_f32 v[180:181], v[138:139], v[180:181]
	v_pk_mul_f32 v[166:167], v[180:181], v[166:167]
	v_cvt_pk_bf16_f32 v165, v166, v167
	global_store_dwordx2 v[172:173], v[164:165], off offset:8
	v_cndmask_b32_e64 v164, v96, v104, s[6:7]
	s_nop 1
	v_mov_b32_dpp v168, v164 row_ror:1 row_mask:0xf bank_mask:0xf
	v_cndmask_b32_e64 v164, v64, v72, s[6:7]
	v_cndmask_b32_e64 v165, v98, v106, s[6:7]
	s_nop 0
	v_mov_b32_dpp v194, v164 row_ror:1 row_mask:0xf bank_mask:0xf
	v_cndmask_b32_e64 v164, v97, v105, s[6:7]
	v_cndmask_b32_e64 v167, v99, v107, s[6:7]
	s_nop 0
	v_mov_b32_dpp v169, v164 row_ror:1 row_mask:0xf bank_mask:0xf
	v_cndmask_b32_e64 v164, v65, v73, s[6:7]
	s_nop 1
	v_mov_b32_dpp v195, v164 row_ror:1 row_mask:0xf bank_mask:0xf
	v_mov_b32_dpp v164, v165 row_ror:1 row_mask:0xf bank_mask:0xf
	v_cndmask_b32_e64 v165, v66, v74, s[6:7]
	v_mov_b32_dpp v181, v183 row_ror:1 row_mask:0xf bank_mask:0xf
	s_nop 0
	v_mov_b32_dpp v180, v165 row_ror:1 row_mask:0xf bank_mask:0xf
	v_mov_b32_dpp v172, v96 row_ror:15 row_mask:0xf bank_mask:0xf
	v_mov_b32_dpp v173, v97 row_ror:15 row_mask:0xf bank_mask:0xf
	v_mov_b32_dpp v165, v167 row_ror:1 row_mask:0xf bank_mask:0xf
	v_mov_b32_dpp v166, v98 row_ror:15 row_mask:0xf bank_mask:0xf
	v_mov_b32_dpp v182, v66 row_ror:15 row_mask:0xf bank_mask:0xf
	v_mov_b32_dpp v167, v99 row_ror:15 row_mask:0xf bank_mask:0xf
	v_mov_b32_dpp v183, v67 row_ror:15 row_mask:0xf bank_mask:0xf
	s_and_saveexec_b64 s[44:45], s[8:9]
	s_cbranch_execz .LBB0_135
	v_pk_mul_f32 v[202:203], v[64:65], v[152:153]
	v_pk_mul_f32 v[200:201], v[96:97], v[156:157]
	v_pk_fma_f32 v[194:195], v[140:141], v[194:195], v[202:203]
	v_pk_fma_f32 v[168:169], v[128:129], v[168:169], v[200:201]
	v_pk_fma_f32 v[194:195], v[144:145], v[196:197], v[194:195]
	v_pk_fma_f32 v[168:169], v[132:133], v[172:173], v[168:169]
	v_pk_add_f32 v[194:195], v[148:149], v[194:195]
	v_pk_add_f32 v[168:169], v[136:137], v[168:169]
	v_mul_f32_e32 v196, 0xbfb8aa3b, v194
	v_exp_f32_e32 v202, v196
	v_mul_f32_e32 v196, 0xbfb8aa3b, v195
	v_exp_f32_e32 v203, v196
	v_pk_mul_f32 v[196:197], v[66:67], v[154:155]
	v_add_f32_e32 v202, 1.0, v202
	v_pk_fma_f32 v[180:181], v[142:143], v[180:181], v[196:197]
	v_add_f32_e32 v203, 1.0, v203
	v_pk_fma_f32 v[180:181], v[146:147], v[182:183], v[180:181]
	v_rcp_f32_e32 v202, v202
	v_pk_add_f32 v[180:181], v[150:151], v[180:181]
	v_rcp_f32_e32 v203, v203
	v_mul_f32_e32 v182, 0xbfb8aa3b, v180
	v_mul_f32_e32 v183, 0xbfb8aa3b, v181
	v_exp_f32_e32 v182, v182
	v_exp_f32_e32 v183, v183
	v_pk_mul_f32 v[172:173], v[194:195], v[202:203]
	v_pk_mul_f32 v[198:199], v[98:99], v[158:159]
	v_pk_mul_f32 v[168:169], v[168:169], v[172:173]
	v_add_f32_e32 v172, 1.0, v182
	v_add_f32_e32 v173, 1.0, v183
	v_rcp_f32_e32 v172, v172
	v_rcp_f32_e32 v173, v173
	v_pk_fma_f32 v[164:165], v[130:131], v[164:165], v[198:199]
	v_readlane_b32 s46, v254, 39
	v_pk_fma_f32 v[164:165], v[134:135], v[166:167], v[164:165]
	v_pk_mul_f32 v[166:167], v[180:181], v[172:173]
	v_pk_add_f32 v[164:165], v[138:139], v[164:165]
	v_readlane_b32 s47, v254, 40
	v_pk_mul_f32 v[164:165], v[164:165], v[166:167]
	s_movk_i32 s0, 0x2c00
	v_cvt_pk_bf16_f32 v167, v164, v165
	v_mov_b64_e32 v[164:165], s[46:47]
	v_mad_i64_i32 v[164:165], s[46:47], v217, s0, v[164:165]
	v_cvt_pk_bf16_f32 v166, v168, v169
	v_lshl_add_u64 v[164:165], v[162:163], 1, v[164:165]
	global_store_dwordx2 v[164:165], v[166:167], off offset:8

; DI unsigned pk2(float lo, float hi) { f32x2 v = {lo, hi}; return __builtin_bit_cast(unsigned, __builtin_convertvector(v, bf16x2v)); }
; DI float dpp_ror1(float v) { return __builtin_bit_cast(float, __builtin_amdgcn_update_dpp(0, __builtin_bit_cast(int, v), 0x121, 0xF, 0xF, false)); }
;     DI void operator()(const f32x4 (&acc)[2][2][4][2], const Unit& u, int wr, int wc, int fr, int fq) const {
;     ...
;             const int ca = colA + 4 * n;
;             const f32x4 wa0 = *(const f32x4*)(cw + ca), wa1 = *(const f32x4*)(cw + DFF2 + ca), wa2 = *(const f32x4*)(cw + 2 * DFF2 + ca), ba = *(const f32x4*)(cb + ca);
;             const f32x4 wg0 = *(const f32x4*)(cw + DFF + ca), wg1 = *(const f32x4*)(cw + DFF2 + DFF + ca), wg2 = *(const f32x4*)(cw + 2 * DFF2 + DFF + ca), bg = *(const f32x4*)(cb + DFF + ca);
; #pragma unroll
;             for (int ai = 0; ai < 2; ++ai) {
;                 const int sg = 4 * u.pm + 2 * ai + wr, row0 = 64 * sg;
; #pragma unroll
;                 for (int m = 0; m < 4; ++m) {
;                     const int rho = 16 * m + fr;
;                     const f32x4 ca_ = acc[ai][0][m][n], cg_ = acc[ai][1][m][n];
;                     const f32x4 ua_ = acc[ai][0][m > 0 ? m - 1 : 0][n], ug_ = acc[ai][1][m > 0 ? m - 1 : 0][n];
;                     const f32x4 da_ = acc[ai][0][m < 3 ? m + 1 : 3][n], dg_ = acc[ai][1][m < 3 ? m + 1 : 3][n];
;                     float o[4];
; #pragma unroll
;                     for (int j = 0; j < 4; ++j) {
;                         const float upa = dpp_ror1(fr == 15 ? ua_[j] : ca_[j]), dna = dpp_rol1(fr == 0 ? da_[j] : ca_[j]);
;                         const float upg = dpp_ror1(fr == 15 ? ug_[j] : cg_[j]), dng = dpp_rol1(fr == 0 ? dg_[j] : cg_[j]);
;                         const float va = wa0[j] * upa + wa1[j] * ca_[j] + wa2[j] * dna + ba[j];
;                         const float vg = wg0[j] * upg + wg1[j] * cg_[j] + wg2[j] * dng + bg[j];
;                         const float sgm = vg * __builtin_amdgcn_rcpf(1.f + __builtin_amdgcn_exp2f(-vg * LOG2E));
;                         o[j] = sgm * va;
;                     }
;                     if (rho >= 1 && rho <= 62) { u32x2 w; w.x = pk2(o[0], o[1]); w.y = pk2(o[2], o[3]); *(u32x2*)(ACT + (size_t)(row0 + rho) * DFF + ca) = w; }
.LBB0_137:
	s_or_b64 exec, exec, s[44:45]
	v_cndmask_b32_e64 v164, v56, v48, s[10:11]
	s_nop 1
	v_mov_b32_dpp v170, v164 row_ror:15 row_mask:0xf bank_mask:0xf
	v_cndmask_b32_e64 v164, v24, v16, s[10:11]
	v_cndmask_b32_e64 v165, v58, v50, s[10:11]
	s_nop 0
	v_mov_b32_dpp v194, v164 row_ror:15 row_mask:0xf bank_mask:0xf
	v_cndmask_b32_e64 v164, v57, v49, s[10:11]
	v_mov_b32_dpp v166, v165 row_ror:15 row_mask:0xf bank_mask:0xf
	s_nop 0
	v_mov_b32_dpp v171, v164 row_ror:15 row_mask:0xf bank_mask:0xf
	v_cndmask_b32_e64 v164, v25, v17, s[10:11]
	v_cndmask_b32_e64 v165, v26, v18, s[10:11]
	v_cndmask_b32_e64 v173, v59, v51, s[10:11]
	v_mov_b32_dpp v195, v164 row_ror:15 row_mask:0xf bank_mask:0xf
	v_mov_b32_dpp v180, v165 row_ror:15 row_mask:0xf bank_mask:0xf
	v_mov_b32_dpp v167, v173 row_ror:15 row_mask:0xf bank_mask:0xf
	v_cndmask_b32_e64 v196, v27, v19, s[10:11]
	v_mov_b32_dpp v168, v56 row_ror:1 row_mask:0xf bank_mask:0xf
	v_mov_b32_dpp v182, v24 row_ror:1 row_mask:0xf bank_mask:0xf
	v_mov_b32_dpp v169, v57 row_ror:1 row_mask:0xf bank_mask:0xf
	v_mov_b32_dpp v183, v25 row_ror:1 row_mask:0xf bank_mask:0xf
	v_mov_b32_dpp v164, v58 row_ror:1 row_mask:0xf bank_mask:0xf
	v_mov_b32_dpp v172, v26 row_ror:1 row_mask:0xf bank_mask:0xf
	v_mov_b32_dpp v165, v59 row_ror:1 row_mask:0xf bank_mask:0xf
	v_mov_b32_dpp v173, v27 row_ror:1 row_mask:0xf bank_mask:0xf
	v_mov_b32_dpp v181, v196 row_ror:15 row_mask:0xf bank_mask:0xf
	s_and_saveexec_b64 s[44:45], s[12:13]
	s_cbranch_execz .LBB0_139
	v_pk_mul_f32 v[200:201], v[24:25], v[152:153]
	v_pk_mul_f32 v[198:199], v[56:57], v[156:157]
	v_pk_fma_f32 v[182:183], v[140:141], v[182:183], v[200:201]
	v_pk_fma_f32 v[168:169], v[128:129], v[168:169], v[198:199]
	v_pk_fma_f32 v[182:183], v[144:145], v[194:195], v[182:183]
	v_pk_fma_f32 v[168:169], v[132:133], v[170:171], v[168:169]
	v_pk_add_f32 v[182:183], v[148:149], v[182:183]
	v_pk_add_f32 v[168:169], v[136:137], v[168:169]
	v_mul_f32_e32 v194, 0xbfb8aa3b, v182
	v_exp_f32_e32 v200, v194
	v_mul_f32_e32 v194, 0xbfb8aa3b, v183
	v_exp_f32_e32 v201, v194
	v_pk_mul_f32 v[194:195], v[26:27], v[154:155]
	v_add_f32_e32 v200, 1.0, v200
	v_pk_fma_f32 v[172:173], v[142:143], v[172:173], v[194:195]
	v_add_f32_e32 v201, 1.0, v201
	v_pk_fma_f32 v[172:173], v[146:147], v[180:181], v[172:173]
	v_rcp_f32_e32 v200, v200
	v_pk_add_f32 v[172:173], v[150:151], v[172:173]
	v_rcp_f32_e32 v201, v201
	v_mul_f32_e32 v180, 0xbfb8aa3b, v172
	v_mul_f32_e32 v181, 0xbfb8aa3b, v173
	v_exp_f32_e32 v180, v180
	v_exp_f32_e32 v181, v181
	v_pk_mul_f32 v[170:171], v[182:183], v[200:201]
	v_pk_mul_f32 v[196:197], v[58:59], v[158:159]
	v_pk_mul_f32 v[168:169], v[168:169], v[170:171]
	v_add_f32_e32 v170, 1.0, v180
	v_add_f32_e32 v171, 1.0, v181
	v_rcp_f32_e32 v170, v170
	v_rcp_f32_e32 v171, v171
	v_pk_fma_f32 v[164:165], v[130:131], v[164:165], v[196:197]
	v_readlane_b32 s46, v254, 39
	v_pk_fma_f32 v[164:165], v[134:135], v[166:167], v[164:165]
	v_pk_mul_f32 v[166:167], v[172:173], v[170:171]
	v_pk_add_f32 v[164:165], v[138:139], v[164:165]
	v_readlane_b32 s47, v254, 40
	v_pk_mul_f32 v[164:165], v[164:165], v[166:167]
	s_movk_i32 s0, 0x2c00
	v_cvt_pk_bf16_f32 v167, v164, v165
	v_mov_b64_e32 v[164:165], s[46:47]
	v_mad_i64_i32 v[164:165], s[46:47], v218, s0, v[164:165]
	v_cvt_pk_bf16_f32 v166, v168, v169
	v_lshl_add_u64 v[164:165], v[162:163], 1, v[164:165]
	global_store_dwordx2 v[164:165], v[166:167], off offset:8

; DI unsigned pk2(float lo, float hi) { f32x2 v = {lo, hi}; return __builtin_bit_cast(unsigned, __builtin_convertvector(v, bf16x2v)); }
; DI float dpp_ror1(float v) { return __builtin_bit_cast(float, __builtin_amdgcn_update_dpp(0, __builtin_bit_cast(int, v), 0x121, 0xF, 0xF, false)); }
; DI float dpp_rol1(float v) { return __builtin_bit_cast(float, __builtin_amdgcn_update_dpp(0, __builtin_bit_cast(int, v), 0x12F, 0xF, 0xF, false)); }
;     DI void operator()(const f32x4 (&acc)[2][2][4][2], const Unit& u, int wr, int wc, int fr, int fq) const {
;     ...
;                 for (int m = 0; m < 4; ++m) {
;                     const int rho = 16 * m + fr;
;                     const f32x4 ca_ = acc[ai][0][m][n], cg_ = acc[ai][1][m][n];
;                     const f32x4 ua_ = acc[ai][0][m > 0 ? m - 1 : 0][n], ug_ = acc[ai][1][m > 0 ? m - 1 : 0][n];
;                     const f32x4 da_ = acc[ai][0][m < 3 ? m + 1 : 3][n], dg_ = acc[ai][1][m < 3 ? m + 1 : 3][n];
;                     float o[4];
; #pragma unroll
;                     for (int j = 0; j < 4; ++j) {
;                         const float upa = dpp_ror1(fr == 15 ? ua_[j] : ca_[j]), dna = dpp_rol1(fr == 0 ? da_[j] : ca_[j]);
;                         const float upg = dpp_ror1(fr == 15 ? ug_[j] : cg_[j]), dng = dpp_rol1(fr == 0 ? dg_[j] : cg_[j]);
;                         const float va = wa0[j] * upa + wa1[j] * ca_[j] + wa2[j] * dna + ba[j];
;                         const float vg = wg0[j] * upg + wg1[j] * cg_[j] + wg2[j] * dng + bg[j];
;                         const float sgm = vg * __builtin_amdgcn_rcpf(1.f + __builtin_amdgcn_exp2f(-vg * LOG2E));
;                         o[j] = sgm * va;
;                     }
;                     if (rho >= 1 && rho <= 62) { u32x2 w; w.x = pk2(o[0], o[1]); w.y = pk2(o[2], o[3]); *(u32x2*)(ACT + (size_t)(row0 + rho) * DFF + ca) = w; }
.LBB0_141:
	s_or_b64 exec, exec, s[44:45]
	v_cndmask_b32_e64 v165, v48, v56, s[6:7]
	s_nop 1
	v_mov_b32_dpp v164, v165 row_ror:1 row_mask:0xf bank_mask:0xf
	v_cndmask_b32_e64 v165, v48, v40, s[10:11]
	v_cndmask_b32_e64 v167, v49, v57, s[6:7]
	s_nop 0
	v_mov_b32_dpp v166, v165 row_ror:15 row_mask:0xf bank_mask:0xf
	v_cndmask_b32_e64 v165, v16, v24, s[6:7]
	v_cndmask_b32_e64 v169, v49, v41, s[10:11]
	v_cndmask_b32_e64 v171, v17, v25, s[6:7]
	v_mov_b32_dpp v168, v165 row_ror:1 row_mask:0xf bank_mask:0xf
	v_cndmask_b32_e64 v165, v16, v8, s[10:11]
	v_cndmask_b32_e64 v172, v17, v9, s[10:11]
	v_pk_mul_f32 v[200:201], v[16:17], v[152:153]
	v_mov_b32_dpp v170, v165 row_ror:15 row_mask:0xf bank_mask:0xf
	v_cndmask_b32_e64 v173, v50, v58, s[6:7]
	v_mov_b32_dpp v165, v167 row_ror:1 row_mask:0xf bank_mask:0xf
	v_mov_b32_dpp v167, v169 row_ror:15 row_mask:0xf bank_mask:0xf
	v_cndmask_b32_e64 v181, v51, v59, s[6:7]
	v_cndmask_b32_e64 v183, v51, v43, s[10:11]
	v_mov_b32_dpp v169, v171 row_ror:1 row_mask:0xf bank_mask:0xf
	v_pk_fma_f32 v[168:169], v[140:141], v[168:169], v[200:201]
	v_cndmask_b32_e64 v195, v19, v27, s[6:7]
	v_mov_b32_dpp v171, v172 row_ror:15 row_mask:0xf bank_mask:0xf
	v_pk_fma_f32 v[168:169], v[144:145], v[170:171], v[168:169]
	v_pk_add_f32 v[168:169], v[148:149], v[168:169]
	v_pk_mul_f32 v[198:199], v[48:49], v[156:157]
	v_mul_f32_e32 v170, 0xbfb8aa3b, v168
	v_exp_f32_e32 v200, v170
	v_mul_f32_e32 v170, 0xbfb8aa3b, v169
	v_exp_f32_e32 v201, v170
	v_mov_b32_dpp v172, v173 row_ror:1 row_mask:0xf bank_mask:0xf
	v_cndmask_b32_e64 v173, v50, v42, s[10:11]
	v_add_f32_e32 v200, 1.0, v200
	v_add_f32_e32 v201, 1.0, v201
	v_mov_b32_dpp v180, v173 row_ror:15 row_mask:0xf bank_mask:0xf
	v_cndmask_b32_e64 v173, v18, v26, s[6:7]
	v_rcp_f32_e32 v200, v200
	v_rcp_f32_e32 v201, v201
	v_mov_b32_dpp v182, v173 row_ror:1 row_mask:0xf bank_mask:0xf
	v_cndmask_b32_e64 v173, v18, v10, s[10:11]
	v_cndmask_b32_e64 v196, v19, v11, s[10:11]
	v_pk_mul_f32 v[170:171], v[18:19], v[154:155]
	v_mov_b32_dpp v194, v173 row_ror:15 row_mask:0xf bank_mask:0xf
	v_pk_fma_f32 v[164:165], v[128:129], v[164:165], v[198:199]
	v_pk_mul_f32 v[198:199], v[40:41], v[156:157]
	v_mov_b32_dpp v173, v181 row_ror:1 row_mask:0xf bank_mask:0xf
	v_pk_fma_f32 v[164:165], v[132:133], v[166:167], v[164:165]
	v_pk_mul_f32 v[166:167], v[168:169], v[200:201]
	v_mov_b32_dpp v181, v183 row_ror:15 row_mask:0xf bank_mask:0xf
	v_pk_add_f32 v[164:165], v[136:137], v[164:165]
	s_nop 0
	v_mov_b32_dpp v183, v195 row_ror:1 row_mask:0xf bank_mask:0xf
	v_pk_fma_f32 v[168:169], v[142:143], v[182:183], v[170:171]
	v_pk_mul_f32 v[164:165], v[164:165], v[166:167]
	v_mov_b32_dpp v195, v196 row_ror:15 row_mask:0xf bank_mask:0xf
	v_pk_fma_f32 v[168:169], v[146:147], v[194:195], v[168:169]
	v_pk_mul_f32 v[196:197], v[50:51], v[158:159]
	v_pk_add_f32 v[168:169], v[150:151], v[168:169]
	v_cvt_pk_bf16_f32 v164, v164, v165
	v_mul_f32_e32 v170, 0xbfb8aa3b, v168
	v_mul_f32_e32 v171, 0xbfb8aa3b, v169
	v_exp_f32_e32 v170, v170
	v_exp_f32_e32 v171, v171
	v_pk_mul_f32 v[194:195], v[8:9], v[152:153]
	v_add_f32_e32 v166, 1.0, v170
	v_add_f32_e32 v167, 1.0, v171
	v_rcp_f32_e32 v166, v166
	v_rcp_f32_e32 v167, v167
	v_pk_fma_f32 v[170:171], v[130:131], v[172:173], v[196:197]
	v_cndmask_b32_e64 v172, v9, v1, s[10:11]
	v_pk_fma_f32 v[170:171], v[134:135], v[180:181], v[170:171]
	v_pk_mul_f32 v[166:167], v[168:169], v[166:167]
	v_pk_add_f32 v[170:171], v[138:139], v[170:171]
	v_pk_mul_f32 v[166:167], v[170:171], v[166:167]
	v_cvt_pk_bf16_f32 v165, v166, v167
	global_store_dwordx2 v[174:175], v[164:165], off offset:8
	v_cndmask_b32_e64 v165, v40, v48, s[6:7]
	v_cndmask_b32_e64 v167, v41, v49, s[6:7]
	s_nop 0
	v_mov_b32_dpp v164, v165 row_ror:1 row_mask:0xf bank_mask:0xf
	v_cndmask_b32_e64 v165, v40, v32, s[10:11]
	v_cndmask_b32_e64 v169, v41, v33, s[10:11]
	v_cndmask_b32_e64 v171, v9, v17, s[6:7]
	v_mov_b32_dpp v166, v165 row_ror:15 row_mask:0xf bank_mask:0xf
	v_cndmask_b32_e64 v165, v8, v16, s[6:7]
	v_cndmask_b32_e64 v173, v42, v50, s[6:7]
	s_nop 0
	v_mov_b32_dpp v168, v165 row_ror:1 row_mask:0xf bank_mask:0xf
	v_cndmask_b32_e64 v165, v8, v0, s[10:11]
	v_cndmask_b32_e64 v175, v43, v51, s[6:7]
	s_nop 0
	v_mov_b32_dpp v170, v165 row_ror:15 row_mask:0xf bank_mask:0xf
	v_cndmask_b32_e64 v181, v43, v35, s[10:11]
	v_cndmask_b32_e64 v183, v11, v19, s[6:7]
	v_mov_b32_dpp v165, v167 row_ror:1 row_mask:0xf bank_mask:0xf
	v_cndmask_b32_e64 v196, v11, v3, s[10:11]
	v_pk_fma_f32 v[164:165], v[128:129], v[164:165], v[198:199]
	v_mov_b32_dpp v167, v169 row_ror:15 row_mask:0xf bank_mask:0xf
	v_pk_fma_f32 v[164:165], v[132:133], v[166:167], v[164:165]
	s_nop 0
	v_mov_b32_dpp v169, v171 row_ror:1 row_mask:0xf bank_mask:0xf
	v_pk_fma_f32 v[168:169], v[140:141], v[168:169], v[194:195]
	v_pk_add_f32 v[164:165], v[136:137], v[164:165]
	v_mov_b32_dpp v171, v172 row_ror:15 row_mask:0xf bank_mask:0xf
	v_pk_fma_f32 v[168:169], v[144:145], v[170:171], v[168:169]
	v_pk_add_f32 v[168:169], v[148:149], v[168:169]
	s_nop 0
	v_mul_f32_e32 v170, 0xbfb8aa3b, v168
	v_mul_f32_e32 v195, 0xbfb8aa3b, v169
	v_exp_f32_e32 v194, v170
	v_exp_f32_e32 v195, v195
	v_mov_b32_dpp v172, v173 row_ror:1 row_mask:0xf bank_mask:0xf
; DI unsigned pk2(float lo, float hi) { f32x2 v = {lo, hi}; return __builtin_bit_cast(unsigned, __builtin_convertvector(v, bf16x2v)); }
; DI float dpp_ror1(float v) { return __builtin_bit_cast(float, __builtin_amdgcn_update_dpp(0, __builtin_bit_cast(int, v), 0x121, 0xF, 0xF, false)); }
; DI float dpp_rol1(float v) { return __builtin_bit_cast(float, __builtin_amdgcn_update_dpp(0, __builtin_bit_cast(int, v), 0x12F, 0xF, 0xF, false)); }
;     DI void operator()(const f32x4 (&acc)[2][2][4][2], const Unit& u, int wr, int wc, int fr, int fq) const {
;     ...
;                 for (int m = 0; m < 4; ++m) {
;                     const int rho = 16 * m + fr;
;                     const f32x4 ca_ = acc[ai][0][m][n], cg_ = acc[ai][1][m][n];
;                     const f32x4 ua_ = acc[ai][0][m > 0 ? m - 1 : 0][n], ug_ = acc[ai][1][m > 0 ? m - 1 : 0][n];
;                     const f32x4 da_ = acc[ai][0][m < 3 ? m + 1 : 3][n], dg_ = acc[ai][1][m < 3 ? m + 1 : 3][n];
;                     float o[4];
; #pragma unroll
;                     for (int j = 0; j < 4; ++j) {
;                         const float upa = dpp_ror1(fr == 15 ? ua_[j] : ca_[j]), dna = dpp_rol1(fr == 0 ? da_[j] : ca_[j]);
;                         const float upg = dpp_ror1(fr == 15 ? ug_[j] : cg_[j]), dng = dpp_rol1(fr == 0 ? dg_[j] : cg_[j]);
;                         const float va = wa0[j] * upa + wa1[j] * ca_[j] + wa2[j] * dna + ba[j];
;                         const float vg = wg0[j] * upg + wg1[j] * cg_[j] + wg2[j] * dng + bg[j];
;                         const float sgm = vg * __builtin_amdgcn_rcpf(1.f + __builtin_amdgcn_exp2f(-vg * LOG2E));
;                         o[j] = sgm * va;
;                     }
;                     if (rho >= 1 && rho <= 62) { u32x2 w; w.x = pk2(o[0], o[1]); w.y = pk2(o[2], o[3]); *(u32x2*)(ACT + (size_t)(row0 + rho) * DFF + ca) = w; }
;                     if (m == 0 || m == 3) {
;                         if (rho <= 1 || rho >= 62) { const int slot = rho <= 1 ? rho : rho - 60;
;                             bf16_t* rp = RAW + ((size_t)sg * 4 + slot) * DFF2 + ca;
;                             u32x2 wa; wa.x = pk2(ca_[0], ca_[1]); wa.y = pk2(ca_[2], ca_[3]); *(u32x2*)rp = wa;
;                             u32x2 wg; wg.x = pk2(cg_[0], cg_[1]); wg.y = pk2(cg_[2], cg_[3]); *(u32x2*)(rp + DFF) = wg; }
	v_cndmask_b32_e64 v173, v42, v34, s[10:11]
	v_add_f32_e32 v194, 1.0, v194
	v_add_f32_e32 v195, 1.0, v195
	v_mov_b32_dpp v174, v173 row_ror:15 row_mask:0xf bank_mask:0xf
	v_cndmask_b32_e64 v173, v10, v18, s[6:7]
	v_rcp_f32_e32 v194, v194
	v_rcp_f32_e32 v195, v195
	v_mov_b32_dpp v180, v173 row_ror:1 row_mask:0xf bank_mask:0xf
	v_cndmask_b32_e64 v173, v10, v2, s[10:11]
	v_pk_mul_f32 v[170:171], v[10:11], v[154:155]
	v_pk_mul_f32 v[166:167], v[168:169], v[194:195]
	v_mov_b32_dpp v182, v173 row_ror:15 row_mask:0xf bank_mask:0xf
	v_pk_mul_f32 v[164:165], v[164:165], v[166:167]
	s_nop 0
	v_mov_b32_dpp v173, v175 row_ror:1 row_mask:0xf bank_mask:0xf
	v_cvt_pk_bf16_f32 v164, v164, v165
	s_nop 0
	v_mov_b32_dpp v175, v181 row_ror:15 row_mask:0xf bank_mask:0xf
	s_nop 1
	v_mov_b32_dpp v181, v183 row_ror:1 row_mask:0xf bank_mask:0xf
	v_pk_fma_f32 v[168:169], v[142:143], v[180:181], v[170:171]
	v_mov_b32_dpp v183, v196 row_ror:15 row_mask:0xf bank_mask:0xf
	v_pk_fma_f32 v[168:169], v[146:147], v[182:183], v[168:169]
	v_pk_mul_f32 v[196:197], v[42:43], v[158:159]
	v_pk_add_f32 v[168:169], v[150:151], v[168:169]
	v_mul_f32_e32 v170, 0xbfb8aa3b, v168
	v_mul_f32_e32 v171, 0xbfb8aa3b, v169
	v_exp_f32_e32 v170, v170
	v_exp_f32_e32 v171, v171
	v_mov_b32_dpp v180, v0 row_ror:15 row_mask:0xf bank_mask:0xf
	v_mov_b32_dpp v181, v1 row_ror:15 row_mask:0xf bank_mask:0xf
	v_add_f32_e32 v166, 1.0, v170
	v_add_f32_e32 v167, 1.0, v171
	v_rcp_f32_e32 v166, v166
	v_rcp_f32_e32 v167, v167
	v_pk_fma_f32 v[170:171], v[130:131], v[172:173], v[196:197]
	v_pk_fma_f32 v[170:171], v[134:135], v[174:175], v[170:171]
	v_pk_mul_f32 v[166:167], v[168:169], v[166:167]
	v_pk_add_f32 v[170:171], v[138:139], v[170:171]
	v_pk_mul_f32 v[166:167], v[170:171], v[166:167]
	v_cvt_pk_bf16_f32 v165, v166, v167
	global_store_dwordx2 v[178:179], v[164:165], off offset:8
	v_cndmask_b32_e64 v164, v32, v40, s[6:7]
	s_nop 1
	v_mov_b32_dpp v168, v164 row_ror:1 row_mask:0xf bank_mask:0xf
	v_cndmask_b32_e64 v164, v0, v8, s[6:7]
	v_cndmask_b32_e64 v165, v34, v42, s[6:7]
	v_cndmask_b32_e64 v167, v35, v43, s[6:7]
	v_mov_b32_dpp v178, v164 row_ror:1 row_mask:0xf bank_mask:0xf
	v_cndmask_b32_e64 v164, v33, v41, s[6:7]
	v_cndmask_b32_e64 v175, v3, v11, s[6:7]
	s_nop 0
	v_mov_b32_dpp v169, v164 row_ror:1 row_mask:0xf bank_mask:0xf
	v_cndmask_b32_e64 v164, v1, v9, s[6:7]
	s_nop 1
	v_mov_b32_dpp v179, v164 row_ror:1 row_mask:0xf bank_mask:0xf
	v_mov_b32_dpp v164, v165 row_ror:1 row_mask:0xf bank_mask:0xf
	v_cndmask_b32_e64 v165, v2, v10, s[6:7]
	v_mov_b32_dpp v173, v175 row_ror:1 row_mask:0xf bank_mask:0xf
	s_nop 0
	v_mov_b32_dpp v172, v165 row_ror:1 row_mask:0xf bank_mask:0xf
	v_mov_b32_dpp v170, v32 row_ror:15 row_mask:0xf bank_mask:0xf
	v_mov_b32_dpp v171, v33 row_ror:15 row_mask:0xf bank_mask:0xf
	v_mov_b32_dpp v165, v167 row_ror:1 row_mask:0xf bank_mask:0xf
	v_mov_b32_dpp v166, v34 row_ror:15 row_mask:0xf bank_mask:0xf
	v_mov_b32_dpp v174, v2 row_ror:15 row_mask:0xf bank_mask:0xf
	v_mov_b32_dpp v167, v35 row_ror:15 row_mask:0xf bank_mask:0xf
	v_mov_b32_dpp v175, v3 row_ror:15 row_mask:0xf bank_mask:0xf
	s_and_saveexec_b64 s[44:45], s[8:9]
	s_cbranch_execz .LBB0_144
	v_pk_mul_f32 v[152:153], v[0:1], v[152:153]
	v_pk_mul_f32 v[156:157], v[32:33], v[156:157]
	v_pk_fma_f32 v[140:141], v[140:141], v[178:179], v[152:153]
	v_pk_fma_f32 v[128:129], v[128:129], v[168:169], v[156:157]
	v_pk_fma_f32 v[140:141], v[144:145], v[180:181], v[140:141]
	v_pk_fma_f32 v[128:129], v[132:133], v[170:171], v[128:129]
	v_pk_add_f32 v[140:141], v[148:149], v[140:141]
	v_pk_add_f32 v[128:129], v[136:137], v[128:129]
	v_mul_f32_e32 v144, 0xbfb8aa3b, v140
	v_exp_f32_e32 v148, v144
	v_mul_f32_e32 v144, 0xbfb8aa3b, v141
	v_exp_f32_e32 v149, v144
	v_pk_mul_f32 v[144:145], v[2:3], v[154:155]
	v_add_f32_e32 v148, 1.0, v148
	v_rcp_f32_e32 v148, v148
	v_add_f32_e32 v149, 1.0, v149
	v_rcp_f32_e32 v149, v149
	v_pk_fma_f32 v[136:137], v[142:143], v[172:173], v[144:145]
	v_pk_mul_f32 v[158:159], v[34:35], v[158:159]
	v_pk_fma_f32 v[136:137], v[146:147], v[174:175], v[136:137]
	v_pk_mul_f32 v[132:133], v[140:141], v[148:149]
	v_pk_add_f32 v[136:137], v[150:151], v[136:137]
	v_pk_mul_f32 v[128:129], v[128:129], v[132:133]
	v_mul_f32_e32 v140, 0xbfb8aa3b, v136
	v_mul_f32_e32 v141, 0xbfb8aa3b, v137
	v_exp_f32_e32 v140, v140
	v_exp_f32_e32 v141, v141
	v_pk_fma_f32 v[130:131], v[130:131], v[164:165], v[158:159]
	v_readlane_b32 s46, v254, 39
	v_add_f32_e32 v132, 1.0, v140
	v_add_f32_e32 v133, 1.0, v141
	v_rcp_f32_e32 v132, v132
	v_rcp_f32_e32 v133, v133
	v_pk_fma_f32 v[130:131], v[134:135], v[166:167], v[130:131]
	v_readlane_b32 s47, v254, 40
	v_pk_add_f32 v[130:131], v[138:139], v[130:131]
	v_pk_mul_f32 v[132:133], v[136:137], v[132:133]
	v_cvt_pk_bf16_f32 v128, v128, v129
	v_pk_mul_f32 v[130:131], v[130:131], v[132:133]
	s_movk_i32 s0, 0x2c00
	v_cvt_pk_bf16_f32 v129, v130, v131
	v_mov_b64_e32 v[130:131], s[46:47]
	v_mad_i64_i32 v[130:131], s[46:47], v220, s0, v[130:131]
	v_lshl_add_u64 v[130:131], v[162:163], 1, v[130:131]
	global_store_dwordx2 v[130:131], v[128:129], off offset:8
	s_or_b64 exec, exec, s[44:45]
	s_and_saveexec_b64 s[44:45], s[16:17]
	s_cbranch_execnz .LBB0_145

; #define LAS __attribute__((address_space(3)))
; __device__ __forceinline__ unsigned xb_add(unsigned* p, unsigned v) { return __hip_atomic_fetch_add(p, v, __ATOMIC_RELAXED, __HIP_MEMORY_SCOPE_AGENT); }
; __device__ __forceinline__ unsigned xb_xcc_id() { return (unsigned)__builtin_amdgcn_s_getreg((3 << 11) | 20) & 0xFu; }
; __device__ __forceinline__ void xcd_barrier(const XcdBarrier& b) {
;     asm volatile("s_waitcnt vmcnt(0)" ::: "memory");
;     __syncthreads();
;     if (threadIdx.x == 0) {
;         unsigned* bar = b.bar;
;         __builtin_amdgcn_s_waitcnt(0);
;         unsigned nloc = b.st[0], nx = b.st[1];
;         if (nloc == 0u) { xcd_barrier_complete(bar, b.x, nloc, nx); b.st[0] = nloc; b.st[1] = nx; }
;         const unsigned old = xb_add(&bar[XB_XSUB(b.x)], 1u);
;         const unsigned gen = old / nloc;
; __global__ void __launch_bounds__(512, 2) mega_fwd(Args args_by_value) {
;     ...
;         if (ph + 1 < ph_hi) {
;             if (ph == ph_lo) cg::this_grid().sync();
;             else { XcdBarrier xb; xb.bar = (unsigned*)(ws + WS_BAR); xb.x = xb_xcc_id(); xb.st = (volatile LAS unsigned*)(lds + LDS_MISC); xcd_barrier(xb); }
.LBB0_823:
	v_writelane_b32 v254, s18, 23
	s_add_i32 s48, s96, 1
	s_cmp_ge_i32 s48, s91
	v_writelane_b32 v254, s19, 24
	v_writelane_b32 v254, s16, 25
	s_mov_b64 s[0:1], -1
	s_nop 0
	v_writelane_b32 v254, s17, 26
	s_nop 0
	v_readlane_b32 s60, v254, 17
	v_readlane_b32 s61, v254, 18
	s_cbranch_scc1 .LBB0_14
	s_cmp_lg_u32 s96, s90
	s_nop 0
	s_getreg_b32 s6, hwreg(HW_REG_XCC_ID, 0, 4)
	s_waitcnt vmcnt(0)
	s_waitcnt vmcnt(0) lgkmcnt(0)
	s_barrier
	s_mov_b64 s[0:1], exec
	v_readlane_b32 s8, v254, 3
	v_readlane_b32 s9, v254, 4
	s_and_b64 s[8:9], s[0:1], s[8:9]
	s_mov_b64 exec, s[8:9]
	s_cbranch_execz .LBB0_877
	s_add_i32 s50, 0, 0x20000
	v_mov_b32_e32 v0, s50
	s_waitcnt vmcnt(0) expcnt(0) lgkmcnt(0)
	ds_read_b32 v2, v0
	v_readlane_b32 s7, v254, 2
	s_and_b32 s35, s6, 15
	s_waitcnt lgkmcnt(0)
	v_cmp_ne_u32_e32 vcc, 0, v2
	v_mov_b32_e32 v0, s7
	ds_read_b32 v0, v0
	s_cbranch_vccnz .LBB0_841
	s_load_dwordx2 s[10:11], s[92:93], 0x4
	s_add_u32 s6, s82, 0xdc200
	s_addc_u32 s7, s83, 0
	s_add_u32 s8, s82, 0xdc400
	s_addc_u32 s9, s83, 0
	s_waitcnt lgkmcnt(0)
	s_mul_i32 s58, s10, s3
	s_add_u32 s10, s82, 0xdc500
	s_mul_i32 s58, s58, s11
	s_addc_u32 s11, s83, 0
	s_add_u32 s12, s82, 0xdc600
	s_addc_u32 s13, s83, 0
	s_add_u32 s14, s82, 0xdc700
	s_addc_u32 s15, s83, 0
	s_add_u32 s16, s82, 0xdc800
	s_addc_u32 s17, s83, 0
	s_add_u32 s18, s82, 0xdc900
	s_addc_u32 s19, s83, 0
	s_add_u32 s20, s82, 0xdca00
	s_addc_u32 s21, s83, 0
	s_add_u32 s24, s82, 0xdcb00
	s_addc_u32 s25, s83, 0
	s_add_u32 s26, s82, 0xdcc00
	s_addc_u32 s27, s83, 0
	s_add_u32 s36, s82, 0xdcd00
	s_addc_u32 s37, s83, 0
	s_add_u32 s38, s82, 0xdce00
	s_addc_u32 s39, s83, 0
	s_add_u32 s40, s82, 0xdcf00
	s_addc_u32 s41, s83, 0
	s_add_u32 s44, s82, 0xdd000
	s_addc_u32 s45, s83, 0
	s_add_u32 s46, s82, 0xdd100
	s_addc_u32 s47, s83, 0
	s_add_u32 s54, s82, 0xdd200
	s_addc_u32 s55, s83, 0
	s_add_u32 s62, s82, 0xdd300
	s_addc_u32 s63, s83, 0
	s_mov_b32 s59, 1
	s_branch .LBB0_829
